# k45 + POST rope rotation arms rewritten as 2 v_mul + 2 v_fma (was pk_mul/mov/pk_add shuffle, 8 instrs), 58 arms
# speedup vs baseline: 1.0103x; 1.0049x over previous
; #define LAS __attribute__((address_space(3)))
; DI unsigned pk2(float lo, float hi) { f32x2 x = {lo, hi}; return __builtin_bit_cast(unsigned, __builtin_convertvector(x, bf16x2_t)); }
; DI float sum32(float v) { v += __shfl_xor(v, 16); return sum16(v); }
; DI f32x2 unpk(unsigned w) { f32x2 r = {bflo(w), bfhi(w)}; return r; }
; template <int HP> DI void rope2(f32x2& x, int hl, const LAS f32x2* cs) {
;   const float pa = __shfl_xor(x[0], HP), pb = __shfl_xor(x[1], HP);
;   if (hl < HP) { const f32x2 c0 = cs[2 * hl], c1 = cs[2 * hl + 1]; x[0] = x[0] * c0[0] - pa * c0[1]; x[1] = x[1] * c1[0] - pb * c1[1]; }
;   else if (hl < 2 * HP) { const f32x2 c0 = cs[2 * (hl - HP)], c1 = cs[2 * (hl - HP) + 1]; x[0] = x[0] * c0[0] + pa * c0[1]; x[1] = x[1] * c1[0] + pb * c1[1]; }
; DI void post_unit(const Params& p, int l, int unit, LAS unsigned char* lds) {
;     ...
;   for (int tp = 0; tp < 4; ++tp) {
;     constexpr int segcol[16] = {C_QA, C_QA + 128, C_KA, C_QI, C_QI + 128, C_QI + 256, C_QI + 384, C_KI, C_QB, C_QB + 128, C_KB, C_KB + 128, C_QC, C_QC + 128, C_KC, C_KC + 128};
;     unsigned raw2[2][16];
; #pragma unroll
;     for (int hf = 0; hf < 2; ++hf) { const u16* rowl = proj + (tok0 + w * 8 + 2 * tp + hf) * NP;
; #pragma unroll
;       for (int s = 0; s < 16; ++s) raw2[hf][s] = *(const unsigned*)(rowl + segcol[s] + 2 * lane); }
; #pragma unroll
;     for (int hf = 0; hf < 2; ++hf) {
;     const int t = w * 8 + 2 * tp + hf; u16* row = proj + (tok0 + t) * NP;
; #pragma unroll
;     for (int s = 0; s < 16; ++s) {
;       f32x2 x = unpk(raw2[hf][s]); u16* pp = row + segcol[s] + 2 * lane;
;       if (s < 2) {
;         const float rs = rsqrtf(sum32(x[0] * x[0] + x[1] * x[1]) * (1.0f / 64.0f) + EPS);
;         x[0] *= rs * qna[2 * hl]; x[1] *= rs * qna[2 * hl + 1]; rope2<4>(x, hl, cs16 + t * 8);
;         x *= LOG2E * 0.125f; *(unsigned*)pp = pk2(x[0], x[1]);
.LBB0_150:
	ds_read_b128 v[208:211], v35
	ds_read_b128 v[212:215], v35 offset:64
	ds_read_b128 v[216:219], v39
	ds_read_b128 v[220:223], v39 offset:256
	ds_read_b128 v[224:227], v40
	ds_read_b128 v[228:231], v40 offset:32
	ds_read_b128 v[232:235], v35 offset:128
	ds_read_b128 v[236:239], v39 offset:512
	ds_read_b128 v[240:243], v40 offset:64
	s_waitcnt lgkmcnt(0)
	v_lshl_add_u64 v[18:19], v[12:13], 0, v[0:1]
	v_add_co_u32_e32 v20, vcc, 0xa000000, v18
	s_mov_b32 s2, 0xa001000
	s_waitcnt lgkmcnt(0)
	v_addc_co_u32_e32 v21, vcc, 0, v19, vcc
	global_load_dword v49, v[20:21], off
	v_add_co_u32_e32 v22, vcc, s2, v18
	s_mov_b32 s2, 0xa003000
	s_nop 0
	v_addc_co_u32_e32 v23, vcc, 0, v19, vcc
	v_add_co_u32_e32 v42, vcc, s77, v18
	global_load_dword v59, v[20:21], off offset:512
	global_load_dword v70, v[20:21], off offset:768
	global_load_dword v69, v[20:21], off offset:1024
	global_load_dword v68, v[20:21], off offset:1280
	global_load_dword v67, v[20:21], off offset:1536
	global_load_dword v58, v[20:21], off offset:1792
	global_load_dword v71, v[20:21], off offset:256
	v_addc_co_u32_e32 v43, vcc, 0, v19, vcc
	global_load_dword v56, v[20:21], off offset:2432
	global_load_dword v66, v[20:21], off offset:2688
	global_load_dword v65, v[20:21], off offset:2944
	global_load_dword v64, v[20:21], off offset:3200
	global_load_dword v54, v[22:23], off offset:384
	global_load_dword v63, v[22:23], off offset:640
	global_load_dword v62, v[22:23], off offset:896
	global_load_dword v61, v[22:23], off offset:1152
	v_add_co_u32_e32 v20, vcc, s2, v18
	global_load_dword v60, v[42:43], off offset:512
	global_load_dword v57, v[42:43], off offset:768
	global_load_dword v55, v[42:43], off offset:1024
	global_load_dword v53, v[42:43], off offset:1280
	global_load_dword v52, v[42:43], off offset:1536
	global_load_dword v51, v[42:43], off offset:1792
	global_load_dword v50, v[42:43], off offset:2048
	global_load_dword v48, v[42:43], off offset:2304
	v_addc_co_u32_e32 v21, vcc, 0, v19, vcc
	global_load_dword v47, v[42:43], off offset:2944
	global_load_dword v46, v[42:43], off offset:3200
	global_load_dword v45, v[42:43], off offset:3456
	global_load_dword v44, v[42:43], off offset:3712
	s_nop 0
	global_load_dword v43, v[20:21], off offset:896
	global_load_dword v42, v[20:21], off offset:1152
	global_load_dword v41, v[20:21], off offset:1408
	global_load_dword v3, v[20:21], off offset:1664
	s_waitcnt vmcnt(31)
	v_and_b32_e32 v21, 0xffff0000, v49
	v_lshlrev_b32_e32 v20, 16, v49
	v_pk_mul_f32 v[22:23], v[20:21], v[20:21]
	s_nop 0
	v_add_f32_e32 v22, v22, v23
	v_mov_b32_e32 v23, v22
	s_nop 1
	v_permlane16_swap_b32_e32 v22, v23
	v_add_f32_e32 v22, v22, v23
	s_nop 1
	v_add_f32_dpp v22, v22, v22 row_ror:8 row_mask:0xf bank_mask:0xf
	s_nop 1
	v_add_f32_dpp v22, v22, v22 row_ror:4 row_mask:0xf bank_mask:0xf
	s_nop 1
	v_add_f32_dpp v22, v22, v22 quad_perm:[2,3,0,1] row_mask:0xf bank_mask:0xf
	s_nop 1
	v_add_f32_dpp v22, v22, v22 quad_perm:[1,0,3,2] row_mask:0xf bank_mask:0xf
	v_fmamk_f32 v22, v22, 0x3c800000, v170
	v_mul_f32_e32 v23, 0x4b800000, v22
	v_cmp_gt_f32_e32 vcc, s33, v22
	s_nop 1
	v_cndmask_b32_e32 v22, v22, v23, vcc
	v_rsq_f32_e32 v22, v22
	s_nop 0
	v_mul_f32_e32 v23, 0x45800000, v22
	v_cndmask_b32_e32 v22, v22, v23, vcc
	v_pk_mul_f32 v[22:23], v[4:5], v[22:23] op_sel_hi:[1,0]
	s_nop 0
	v_pk_mul_f32 v[22:23], v[22:23], v[20:21]
	ds_bpermute_b32 v20, v28, v22
	ds_bpermute_b32 v21, v28, v23
	s_and_saveexec_b64 s[2:3], s[12:13]
	s_xor_b64 s[18:19], exec, s[2:3]
	s_cbranch_execz .LBB0_154
	s_and_saveexec_b64 s[30:31], s[14:15]
	s_cbranch_execz .LBB0_153
	v_add_u32_e32 v49, 0, v35
	s_waitcnt lgkmcnt(0)
	v_mul_f32_e32 v22, v22, v208
	v_mul_f32_e32 v23, v23, v210
	v_fmac_f32_e32 v22, v209, v20
	v_fmac_f32_e32 v23, v21, v211

; #define LAS __attribute__((address_space(3)))
; DI unsigned pk2(float lo, float hi) { f32x2 x = {lo, hi}; return __builtin_bit_cast(unsigned, __builtin_convertvector(x, bf16x2_t)); }
; DI float sum32(float v) { v += __shfl_xor(v, 16); return sum16(v); }
; DI f32x2 unpk(unsigned w) { f32x2 r = {bflo(w), bfhi(w)}; return r; }
; template <int HP> DI void rope2(f32x2& x, int hl, const LAS f32x2* cs) {
;   const float pa = __shfl_xor(x[0], HP), pb = __shfl_xor(x[1], HP);
;   if (hl < HP) { const f32x2 c0 = cs[2 * hl], c1 = cs[2 * hl + 1]; x[0] = x[0] * c0[0] - pa * c0[1]; x[1] = x[1] * c1[0] - pb * c1[1]; }
;   else if (hl < 2 * HP) { const f32x2 c0 = cs[2 * (hl - HP)], c1 = cs[2 * (hl - HP) + 1]; x[0] = x[0] * c0[0] + pa * c0[1]; x[1] = x[1] * c1[0] + pb * c1[1]; }
; DI void post_unit(const Params& p, int l, int unit, LAS unsigned char* lds) {
;     ...
;       f32x2 x = unpk(raw2[hf][s]); u16* pp = row + segcol[s] + 2 * lane;
;       if (s < 2) {
;         const float rs = rsqrtf(sum32(x[0] * x[0] + x[1] * x[1]) * (1.0f / 64.0f) + EPS);
;         x[0] *= rs * qna[2 * hl]; x[1] *= rs * qna[2 * hl + 1]; rope2<4>(x, hl, cs16 + t * 8);
;         x *= LOG2E * 0.125f; *(unsigned*)pp = pk2(x[0], x[1]);
.LBB0_154:
	s_or_saveexec_b64 s[18:19], s[18:19]
	v_add_u32_e32 v49, 0, v35
	s_xor_b64 exec, exec, s[18:19]
	s_cbranch_execz .LBB0_156
	s_waitcnt lgkmcnt(0)
	v_mul_f32_e32 v22, v22, v212
	v_mul_f32_e32 v23, v23, v214
	v_fma_f32 v22, -v213, v20, v22
	v_fma_f32 v23, -v21, v215, v23
.LBB0_156:
	s_or_b64 exec, exec, s[18:19]
	s_mov_b64 s[2:3], 0xa000000
	s_waitcnt lgkmcnt(0)
	v_lshl_add_u64 v[20:21], v[18:19], 0, s[2:3]
	s_mov_b32 s2, 0x3e38aa3b
	v_pk_mul_f32 v[22:23], v[22:23], s[2:3] op_sel_hi:[1,0]
	s_nop 0
	v_cvt_pk_bf16_f32 v22, v22, v23
	global_store_dword v[20:21], v22, off
	s_waitcnt vmcnt(25)
	v_and_b32_e32 v21, 0xffff0000, v71
	v_lshlrev_b32_e32 v20, 16, v71
	v_pk_mul_f32 v[22:23], v[20:21], v[20:21]
	s_nop 0
	v_add_f32_e32 v22, v22, v23
	v_mov_b32_e32 v23, v22
	s_nop 1
	v_permlane16_swap_b32_e32 v22, v23
	v_add_f32_e32 v22, v22, v23
	s_nop 1
	v_add_f32_dpp v22, v22, v22 row_ror:8 row_mask:0xf bank_mask:0xf
	s_nop 1
	v_add_f32_dpp v22, v22, v22 row_ror:4 row_mask:0xf bank_mask:0xf
	s_nop 1
	v_add_f32_dpp v22, v22, v22 quad_perm:[2,3,0,1] row_mask:0xf bank_mask:0xf
	s_nop 1
	v_add_f32_dpp v22, v22, v22 quad_perm:[1,0,3,2] row_mask:0xf bank_mask:0xf
	v_fmamk_f32 v22, v22, 0x3c800000, v170
	v_cmp_gt_f32_e32 vcc, s33, v22
	v_mul_f32_e32 v23, 0x4b800000, v22
	s_nop 0
	v_cndmask_b32_e32 v22, v22, v23, vcc
	v_rsq_f32_e32 v22, v22
	s_nop 0
	v_mul_f32_e32 v23, 0x45800000, v22
	v_cndmask_b32_e32 v22, v22, v23, vcc
	v_pk_mul_f32 v[22:23], v[4:5], v[22:23] op_sel_hi:[1,0]
	s_nop 0
	v_pk_mul_f32 v[22:23], v[22:23], v[20:21]
	ds_bpermute_b32 v20, v28, v22
	ds_bpermute_b32 v21, v28, v23
	s_and_saveexec_b64 s[2:3], s[12:13]
	s_xor_b64 s[18:19], exec, s[2:3]
	s_cbranch_execz .LBB0_160
	s_and_saveexec_b64 s[30:31], s[14:15]
	s_cbranch_execz .LBB0_159
	s_waitcnt lgkmcnt(0)
	v_mul_f32_e32 v22, v22, v208
	v_mul_f32_e32 v23, v23, v210
	v_fmac_f32_e32 v22, v209, v20
	v_fmac_f32_e32 v23, v21, v211

; #define LAS __attribute__((address_space(3)))
; DI unsigned pk2(float lo, float hi) { f32x2 x = {lo, hi}; return __builtin_bit_cast(unsigned, __builtin_convertvector(x, bf16x2_t)); }
; DI float sum32(float v) { v += __shfl_xor(v, 16); return sum16(v); }
; DI float sum64(float v) { v += __shfl_xor(v, 32); return sum32(v); }
; DI f32x2 unpk(unsigned w) { f32x2 r = {bflo(w), bfhi(w)}; return r; }
; template <int HP> DI void rope2(f32x2& x, int hl, const LAS f32x2* cs) {
;   const float pa = __shfl_xor(x[0], HP), pb = __shfl_xor(x[1], HP);
;   if (hl < HP) { const f32x2 c0 = cs[2 * hl], c1 = cs[2 * hl + 1]; x[0] = x[0] * c0[0] - pa * c0[1]; x[1] = x[1] * c1[0] - pb * c1[1]; }
;   else if (hl < 2 * HP) { const f32x2 c0 = cs[2 * (hl - HP)], c1 = cs[2 * (hl - HP) + 1]; x[0] = x[0] * c0[0] + pa * c0[1]; x[1] = x[1] * c1[0] + pb * c1[1]; }
; DI void post_unit(const Params& p, int l, int unit, LAS unsigned char* lds) {
;     ...
;       f32x2 x = unpk(raw2[hf][s]); u16* pp = row + segcol[s] + 2 * lane;
;       if (s < 2) {
;         const float rs = rsqrtf(sum32(x[0] * x[0] + x[1] * x[1]) * (1.0f / 64.0f) + EPS);
;         x[0] *= rs * qna[2 * hl]; x[1] *= rs * qna[2 * hl + 1]; rope2<4>(x, hl, cs16 + t * 8);
;         x *= LOG2E * 0.125f; *(unsigned*)pp = pk2(x[0], x[1]);
;       } else if (s == 2) {
;         const float rs = rsqrtf(sum64(x[0] * x[0] + x[1] * x[1]) * (1.0f / 128.0f) + EPS);
;         *(LAS unsigned*)(At + t * 272 + lane * 4) = pk2(x[0] * rs, x[1] * rs);
;       } else if (s < 7) {
;         rope2<4>(x, hl, cs16 + t * 8); *(unsigned*)pp = pk2(x[0], x[1]);
.LBB0_160:
	s_andn2_saveexec_b64 s[18:19], s[18:19]
	s_cbranch_execz .LBB0_162
	s_waitcnt lgkmcnt(0)
	v_mul_f32_e32 v22, v22, v212
	v_mul_f32_e32 v23, v23, v214
	v_fma_f32 v22, -v213, v20, v22
	v_fma_f32 v23, -v21, v215, v23
.LBB0_162:
	s_or_b64 exec, exec, s[18:19]
	s_mov_b64 s[2:3], 0xa000100
	s_waitcnt lgkmcnt(0)
	v_lshl_add_u64 v[20:21], v[18:19], 0, s[2:3]
	s_mov_b32 s2, 0x3e38aa3b
	v_pk_mul_f32 v[22:23], v[22:23], s[2:3] op_sel_hi:[1,0]
	s_nop 0
	v_cvt_pk_bf16_f32 v22, v22, v23
	global_store_dword v[20:21], v22, off
	v_lshlrev_b32_e32 v20, 16, v59
	v_and_b32_e32 v21, 0xffff0000, v59
	v_pk_mul_f32 v[22:23], v[20:21], v[20:21]
	v_add_u32_e32 v59, 0, v33
	v_add_f32_e32 v22, v22, v23
	v_mov_b32_e32 v23, v22
	s_nop 1
	v_permlane32_swap_b32_e32 v22, v23
	v_add_f32_e32 v22, v22, v23
	v_mov_b32_e32 v23, v22
	s_nop 1
	v_permlane16_swap_b32_e32 v22, v23
	v_add_f32_e32 v22, v22, v23
	s_nop 1
	v_add_f32_dpp v22, v22, v22 row_ror:8 row_mask:0xf bank_mask:0xf
	s_nop 1
	v_add_f32_dpp v22, v22, v22 row_ror:4 row_mask:0xf bank_mask:0xf
	s_nop 1
	v_add_f32_dpp v22, v22, v22 quad_perm:[2,3,0,1] row_mask:0xf bank_mask:0xf
	s_nop 1
	v_add_f32_dpp v22, v22, v22 quad_perm:[1,0,3,2] row_mask:0xf bank_mask:0xf
	v_fmamk_f32 v22, v22, 0x3c000000, v170
	v_cmp_gt_f32_e32 vcc, s33, v22
	v_mul_f32_e32 v23, 0x4b800000, v22
	s_nop 0
	v_cndmask_b32_e32 v22, v22, v23, vcc
	v_rsq_f32_e32 v22, v22
	s_nop 0
	v_mul_f32_e32 v23, 0x45800000, v22
	v_cndmask_b32_e32 v22, v22, v23, vcc
	v_pk_mul_f32 v[20:21], v[22:23], v[20:21] op_sel_hi:[0,1]
	v_cvt_pk_bf16_f32 v20, v20, v21
	ds_write_b32 v59, v20
	v_lshlrev_b32_e32 v20, 16, v70
	v_and_b32_e32 v21, 0xffff0000, v70
	ds_bpermute_b32 v70, v28, v20
	ds_bpermute_b32 v23, v28, v21
	s_and_saveexec_b64 s[2:3], s[12:13]
	s_xor_b64 s[18:19], exec, s[2:3]
	s_cbranch_execz .LBB0_166
	s_and_saveexec_b64 s[30:31], s[14:15]
	s_cbranch_execz .LBB0_165
	v_mov_b32_e32 v22, v21
	s_waitcnt lgkmcnt(0)
	v_mul_f32_e32 v20, v208, v20
	v_mul_f32_e32 v21, v210, v22
	v_fmac_f32_e32 v20, v209, v70
	v_fmac_f32_e32 v21, v211, v23

; #define LAS __attribute__((address_space(3)))
; DI unsigned pk2(float lo, float hi) { f32x2 x = {lo, hi}; return __builtin_bit_cast(unsigned, __builtin_convertvector(x, bf16x2_t)); }
; template <int HP> DI void rope2(f32x2& x, int hl, const LAS f32x2* cs) {
;   const float pa = __shfl_xor(x[0], HP), pb = __shfl_xor(x[1], HP);
;   if (hl < HP) { const f32x2 c0 = cs[2 * hl], c1 = cs[2 * hl + 1]; x[0] = x[0] * c0[0] - pa * c0[1]; x[1] = x[1] * c1[0] - pb * c1[1]; }
;   else if (hl < 2 * HP) { const f32x2 c0 = cs[2 * (hl - HP)], c1 = cs[2 * (hl - HP) + 1]; x[0] = x[0] * c0[0] + pa * c0[1]; x[1] = x[1] * c1[0] + pb * c1[1]; }
; DI void post_unit(const Params& p, int l, int unit, LAS unsigned char* lds) {
;     ...
;       } else if (s < 7) {
;         rope2<4>(x, hl, cs16 + t * 8); *(unsigned*)pp = pk2(x[0], x[1]);
.LBB0_166:
	s_andn2_saveexec_b64 s[18:19], s[18:19]
	s_cbranch_execz .LBB0_168
	v_mov_b32_e32 v22, v21
	s_waitcnt lgkmcnt(0)
	v_mul_f32_e32 v20, v212, v20
	v_mul_f32_e32 v21, v214, v22
	v_fma_f32 v20, -v213, v70, v20
	v_fma_f32 v21, -v215, v23, v21
.LBB0_168:
	s_or_b64 exec, exec, s[18:19]
	s_mov_b64 s[2:3], 0xa000300
	s_waitcnt lgkmcnt(0)
	v_lshl_add_u64 v[22:23], v[18:19], 0, s[2:3]
	v_cvt_pk_bf16_f32 v20, v20, v21
	global_store_dword v[22:23], v20, off
	v_lshlrev_b32_e32 v20, 16, v69
	v_and_b32_e32 v21, 0xffff0000, v69
	ds_bpermute_b32 v69, v28, v20
	ds_bpermute_b32 v23, v28, v21
	s_and_saveexec_b64 s[2:3], s[12:13]
	s_xor_b64 s[18:19], exec, s[2:3]
	s_cbranch_execz .LBB0_172
	s_and_saveexec_b64 s[30:31], s[14:15]
	s_cbranch_execz .LBB0_171
	v_mov_b32_e32 v22, v21
	s_waitcnt lgkmcnt(0)
	v_mul_f32_e32 v20, v208, v20
	v_mul_f32_e32 v21, v210, v22
	v_fmac_f32_e32 v20, v209, v69
	v_fmac_f32_e32 v21, v211, v23

; #define LAS __attribute__((address_space(3)))
; DI unsigned pk2(float lo, float hi) { f32x2 x = {lo, hi}; return __builtin_bit_cast(unsigned, __builtin_convertvector(x, bf16x2_t)); }
; template <int HP> DI void rope2(f32x2& x, int hl, const LAS f32x2* cs) {
;   const float pa = __shfl_xor(x[0], HP), pb = __shfl_xor(x[1], HP);
;   if (hl < HP) { const f32x2 c0 = cs[2 * hl], c1 = cs[2 * hl + 1]; x[0] = x[0] * c0[0] - pa * c0[1]; x[1] = x[1] * c1[0] - pb * c1[1]; }
;   else if (hl < 2 * HP) { const f32x2 c0 = cs[2 * (hl - HP)], c1 = cs[2 * (hl - HP) + 1]; x[0] = x[0] * c0[0] + pa * c0[1]; x[1] = x[1] * c1[0] + pb * c1[1]; }
; DI void post_unit(const Params& p, int l, int unit, LAS unsigned char* lds) {
;     ...
;       } else if (s < 7) {
;         rope2<4>(x, hl, cs16 + t * 8); *(unsigned*)pp = pk2(x[0], x[1]);
.LBB0_172:
	s_andn2_saveexec_b64 s[18:19], s[18:19]
	s_cbranch_execz .LBB0_174
	v_mov_b32_e32 v22, v21
	s_waitcnt lgkmcnt(0)
	v_mul_f32_e32 v20, v212, v20
	v_mul_f32_e32 v21, v214, v22
	v_fma_f32 v20, -v213, v69, v20
	v_fma_f32 v21, -v215, v23, v21
.LBB0_174:
	s_or_b64 exec, exec, s[18:19]
	s_mov_b64 s[2:3], 0xa000400
	s_waitcnt lgkmcnt(0)
	v_lshl_add_u64 v[22:23], v[18:19], 0, s[2:3]
	v_cvt_pk_bf16_f32 v20, v20, v21
	global_store_dword v[22:23], v20, off
	v_lshlrev_b32_e32 v20, 16, v68
	v_and_b32_e32 v21, 0xffff0000, v68
	ds_bpermute_b32 v68, v28, v20
	ds_bpermute_b32 v23, v28, v21
	s_and_saveexec_b64 s[2:3], s[12:13]
	s_xor_b64 s[18:19], exec, s[2:3]
	s_cbranch_execz .LBB0_178
	s_and_saveexec_b64 s[30:31], s[14:15]
	s_cbranch_execz .LBB0_177
	v_mov_b32_e32 v22, v21
	s_waitcnt lgkmcnt(0)
	v_mul_f32_e32 v20, v208, v20
	v_mul_f32_e32 v21, v210, v22
	v_fmac_f32_e32 v20, v209, v68
	v_fmac_f32_e32 v21, v211, v23

; #define LAS __attribute__((address_space(3)))
; DI unsigned pk2(float lo, float hi) { f32x2 x = {lo, hi}; return __builtin_bit_cast(unsigned, __builtin_convertvector(x, bf16x2_t)); }
; template <int HP> DI void rope2(f32x2& x, int hl, const LAS f32x2* cs) {
;   const float pa = __shfl_xor(x[0], HP), pb = __shfl_xor(x[1], HP);
;   if (hl < HP) { const f32x2 c0 = cs[2 * hl], c1 = cs[2 * hl + 1]; x[0] = x[0] * c0[0] - pa * c0[1]; x[1] = x[1] * c1[0] - pb * c1[1]; }
;   else if (hl < 2 * HP) { const f32x2 c0 = cs[2 * (hl - HP)], c1 = cs[2 * (hl - HP) + 1]; x[0] = x[0] * c0[0] + pa * c0[1]; x[1] = x[1] * c1[0] + pb * c1[1]; }
; DI void post_unit(const Params& p, int l, int unit, LAS unsigned char* lds) {
;     ...
;       } else if (s < 7) {
;         rope2<4>(x, hl, cs16 + t * 8); *(unsigned*)pp = pk2(x[0], x[1]);
.LBB0_178:
	s_andn2_saveexec_b64 s[18:19], s[18:19]
	s_cbranch_execz .LBB0_180
	v_mov_b32_e32 v22, v21
	s_waitcnt lgkmcnt(0)
	v_mul_f32_e32 v20, v212, v20
	v_mul_f32_e32 v21, v214, v22
	v_fma_f32 v20, -v213, v68, v20
	v_fma_f32 v21, -v215, v23, v21
.LBB0_180:
	s_or_b64 exec, exec, s[18:19]
	s_mov_b64 s[2:3], 0xa000500
	s_waitcnt lgkmcnt(0)
	v_lshl_add_u64 v[22:23], v[18:19], 0, s[2:3]
	v_cvt_pk_bf16_f32 v20, v20, v21
	global_store_dword v[22:23], v20, off
	v_lshlrev_b32_e32 v20, 16, v67
	v_and_b32_e32 v21, 0xffff0000, v67
	ds_bpermute_b32 v67, v28, v20
	ds_bpermute_b32 v23, v28, v21
	s_and_saveexec_b64 s[2:3], s[12:13]
	s_xor_b64 s[18:19], exec, s[2:3]
	s_cbranch_execz .LBB0_184
	s_and_saveexec_b64 s[30:31], s[14:15]
	s_cbranch_execz .LBB0_183
	v_mov_b32_e32 v22, v21
	s_waitcnt lgkmcnt(0)
	v_mul_f32_e32 v20, v208, v20
	v_mul_f32_e32 v21, v210, v22
	v_fmac_f32_e32 v20, v209, v67
	v_fmac_f32_e32 v21, v211, v23

; #define LAS __attribute__((address_space(3)))
; DI unsigned pk2(float lo, float hi) { f32x2 x = {lo, hi}; return __builtin_bit_cast(unsigned, __builtin_convertvector(x, bf16x2_t)); }
; DI float sum32(float v) { v += __shfl_xor(v, 16); return sum16(v); }
; template <int HP> DI void rope2(f32x2& x, int hl, const LAS f32x2* cs) {
;   const float pa = __shfl_xor(x[0], HP), pb = __shfl_xor(x[1], HP);
;   if (hl < HP) { const f32x2 c0 = cs[2 * hl], c1 = cs[2 * hl + 1]; x[0] = x[0] * c0[0] - pa * c0[1]; x[1] = x[1] * c1[0] - pb * c1[1]; }
;   else if (hl < 2 * HP) { const f32x2 c0 = cs[2 * (hl - HP)], c1 = cs[2 * (hl - HP) + 1]; x[0] = x[0] * c0[0] + pa * c0[1]; x[1] = x[1] * c1[0] + pb * c1[1]; }
; DI void post_unit(const Params& p, int l, int unit, LAS unsigned char* lds) {
;     ...
;       } else if (s < 7) {
;         rope2<4>(x, hl, cs16 + t * 8); *(unsigned*)pp = pk2(x[0], x[1]);
;       } else if (s == 7) {
;         const float rs = rsqrtf(sum32(x[0] * x[0] + x[1] * x[1]) * (1.0f / 64.0f) + EPS);
;         x *= rs; rope2<4>(x, hl, cs16 + t * 8); if (lane < 32) *(unsigned*)((u16*)(p.ws + WS_KIC) + (tok0 + t) * 64 + 2 * lane) = pk2(x[0], x[1]);
.LBB0_184:
	s_andn2_saveexec_b64 s[18:19], s[18:19]
	s_cbranch_execz .LBB0_186
	v_mov_b32_e32 v22, v21
	s_waitcnt lgkmcnt(0)
	v_mul_f32_e32 v20, v212, v20
	v_mul_f32_e32 v21, v214, v22
	v_fma_f32 v20, -v213, v67, v20
	v_fma_f32 v21, -v215, v23, v21
.LBB0_186:
	s_or_b64 exec, exec, s[18:19]
	s_mov_b64 s[2:3], 0xa000600
	s_waitcnt lgkmcnt(0)
	v_lshl_add_u64 v[22:23], v[18:19], 0, s[2:3]
	v_cvt_pk_bf16_f32 v20, v20, v21
	global_store_dword v[22:23], v20, off
	v_lshlrev_b32_e32 v20, 16, v58
	v_and_b32_e32 v21, 0xffff0000, v58
	v_pk_mul_f32 v[22:23], v[20:21], v[20:21]
	s_nop 0
	v_add_f32_e32 v22, v22, v23
	v_mov_b32_e32 v23, v22
	s_nop 1
	v_permlane16_swap_b32_e32 v22, v23
	v_add_f32_e32 v22, v22, v23
	s_nop 1
	v_add_f32_dpp v22, v22, v22 row_ror:8 row_mask:0xf bank_mask:0xf
	s_nop 1
	v_add_f32_dpp v22, v22, v22 row_ror:4 row_mask:0xf bank_mask:0xf
	s_nop 1
	v_add_f32_dpp v22, v22, v22 quad_perm:[2,3,0,1] row_mask:0xf bank_mask:0xf
	s_nop 1
	v_add_f32_dpp v22, v22, v22 quad_perm:[1,0,3,2] row_mask:0xf bank_mask:0xf
	v_fmamk_f32 v22, v22, 0x3c800000, v170
	v_cmp_gt_f32_e32 vcc, s33, v22
	v_mul_f32_e32 v23, 0x4b800000, v22
	s_nop 0
	v_cndmask_b32_e32 v22, v22, v23, vcc
	v_rsq_f32_e32 v22, v22
	s_nop 0
	v_mul_f32_e32 v23, 0x45800000, v22
	v_cndmask_b32_e32 v22, v22, v23, vcc
	v_pk_mul_f32 v[20:21], v[22:23], v[20:21] op_sel_hi:[0,1]
	ds_bpermute_b32 v22, v28, v20
	ds_bpermute_b32 v23, v28, v21
	s_and_saveexec_b64 s[2:3], s[12:13]
	s_xor_b64 s[18:19], exec, s[2:3]
	s_cbranch_execz .LBB0_314
	s_and_saveexec_b64 s[30:31], s[14:15]
	s_cbranch_execz .LBB0_189
	s_waitcnt lgkmcnt(0)
	v_mul_f32_e32 v20, v20, v208
	v_mul_f32_e32 v21, v210, v21
	v_fmac_f32_e32 v20, v209, v22
	v_fmac_f32_e32 v21, v211, v23

; #define LAS __attribute__((address_space(3)))
; DI unsigned pk2(float lo, float hi) { f32x2 x = {lo, hi}; return __builtin_bit_cast(unsigned, __builtin_convertvector(x, bf16x2_t)); }
; template <int HP> DI void rope2(f32x2& x, int hl, const LAS f32x2* cs) {
;   const float pa = __shfl_xor(x[0], HP), pb = __shfl_xor(x[1], HP);
;   if (hl < HP) { const f32x2 c0 = cs[2 * hl], c1 = cs[2 * hl + 1]; x[0] = x[0] * c0[0] - pa * c0[1]; x[1] = x[1] * c1[0] - pb * c1[1]; }
;   else if (hl < 2 * HP) { const f32x2 c0 = cs[2 * (hl - HP)], c1 = cs[2 * (hl - HP) + 1]; x[0] = x[0] * c0[0] + pa * c0[1]; x[1] = x[1] * c1[0] + pb * c1[1]; }
; DI void post_unit(const Params& p, int l, int unit, LAS unsigned char* lds) {
;     ...
;       } else if (s < 12) {
;         rope2<16>(x, hl, cs64 + t * 32);
;         const int hd = ((s & 1) ? 2 : 0) + hsel;
;         const float lg = log1pf(-exp2f(-5.0f - (float)hd));
;         const float f = (s < 10) ? expf(lg * (float)(t + 1)) : expf(lg * (float)(63 - t)) * 0.125f;
;         x *= f; *(unsigned*)pp = pk2(x[0], x[1]);
.LBB0_192:
	s_or_b64 exec, exec, s[18:19]
	s_waitcnt vmcnt(29)
	v_lshlrev_b32_e32 v58, 16, v56
	s_waitcnt lgkmcnt(1)
	v_and_b32_e32 v22, 0xffff0000, v56
	ds_bpermute_b32 v67, v26, v58
	s_waitcnt lgkmcnt(1)
	ds_bpermute_b32 v23, v26, v22
	v_add_u32_e32 v56, 0, v39
	s_and_saveexec_b64 s[2:3], s[10:11]
	s_xor_b64 s[18:19], exec, s[2:3]
	s_cbranch_execz .LBB0_194
	s_waitcnt lgkmcnt(0)
	v_mul_f32_e32 v20, v216, v58
	v_mul_f32_e32 v21, v218, v22
	v_fmac_f32_e32 v20, v217, v67
	v_fmac_f32_e32 v21, v219, v23
.LBB0_194:
	s_andn2_saveexec_b64 s[18:19], s[18:19]
	s_cbranch_execz .LBB0_196
	s_waitcnt lgkmcnt(0)
	v_mul_f32_e32 v20, v220, v58
	v_mul_f32_e32 v21, v222, v22
	v_fma_f32 v20, -v221, v67, v20
	v_fma_f32 v21, -v223, v23, v21
.LBB0_196:
	s_or_b64 exec, exec, s[18:19]
	v_add_u32_e32 v58, s36, v2
	s_waitcnt lgkmcnt(1)
	v_add_u32_e32 v67, 1, v58
	v_cvt_f32_i32_e32 v67, v67
	s_mov_b64 s[2:3], 0xa000980
	s_waitcnt lgkmcnt(0)
	v_lshl_add_u64 v[22:23], v[18:19], 0, s[2:3]
	v_mul_f32_e32 v68, v31, v67
	v_mul_f32_e32 v69, 0x3fb8aa3b, v68
	v_fma_f32 v70, v68, s64, -v69
	v_rndne_f32_e32 v71, v69
	v_fmac_f32_e32 v70, 0x32a5705f, v68
	v_sub_f32_e32 v69, v69, v71
	v_add_f32_e32 v69, v69, v70
	v_exp_f32_e32 v69, v69
	v_cvt_i32_f32_e32 v70, v71
	v_cmp_ngt_f32_e32 vcc, s65, v68
	v_ldexp_f32 v69, v69, v70
	s_nop 0
	v_cndmask_b32_e32 v69, 0, v69, vcc
	v_cmp_nlt_f32_e32 vcc, s89, v68
	s_nop 1
	v_cndmask_b32_e32 v68, v177, v69, vcc
	v_pk_mul_f32 v[20:21], v[68:69], v[20:21] op_sel_hi:[0,1]
	v_cvt_pk_bf16_f32 v20, v20, v21
	global_store_dword v[22:23], v20, off
	s_waitcnt vmcnt(29)
	v_lshlrev_b32_e32 v68, 16, v66
	v_and_b32_e32 v20, 0xffff0000, v66
	ds_bpermute_b32 v66, v26, v68
	ds_bpermute_b32 v21, v26, v20
	s_and_saveexec_b64 s[2:3], s[10:11]
	s_xor_b64 s[18:19], exec, s[2:3]
	s_cbranch_execz .LBB0_198
	s_waitcnt lgkmcnt(0)
	v_mul_f32_e32 v22, v216, v68
	v_mul_f32_e32 v23, v218, v20
	v_fmac_f32_e32 v22, v217, v66
	v_fmac_f32_e32 v23, v219, v21
.LBB0_198:
	s_andn2_saveexec_b64 s[18:19], s[18:19]
	s_cbranch_execz .LBB0_200
	s_waitcnt lgkmcnt(0)
	v_mul_f32_e32 v22, v220, v68
	v_mul_f32_e32 v23, v222, v20
	v_fma_f32 v22, -v221, v66, v22
	v_fma_f32 v23, -v223, v21, v23
.LBB0_200:
	s_or_b64 exec, exec, s[18:19]
	s_waitcnt lgkmcnt(1)
	v_mul_f32_e32 v66, v32, v67
	v_mul_f32_e32 v67, 0x3fb8aa3b, v66
	v_fma_f32 v68, v66, s64, -v67
	v_rndne_f32_e32 v69, v67
	v_fmac_f32_e32 v68, 0x32a5705f, v66
	v_sub_f32_e32 v67, v67, v69
	v_add_f32_e32 v67, v67, v68
	v_exp_f32_e32 v67, v67
	v_cvt_i32_f32_e32 v68, v69
	v_cmp_ngt_f32_e32 vcc, s65, v66
	s_mov_b64 s[2:3], 0xa000a80
	s_waitcnt lgkmcnt(0)
	v_lshl_add_u64 v[20:21], v[18:19], 0, s[2:3]
	v_ldexp_f32 v67, v67, v68
	v_cndmask_b32_e32 v67, 0, v67, vcc
	v_cmp_nlt_f32_e32 vcc, s89, v66
	s_nop 1
	v_cndmask_b32_e32 v66, v177, v67, vcc
	v_pk_mul_f32 v[22:23], v[66:67], v[22:23] op_sel_hi:[0,1]
	v_cvt_pk_bf16_f32 v22, v22, v23
	global_store_dword v[20:21], v22, off
	s_waitcnt vmcnt(29)
	v_lshlrev_b32_e32 v66, 16, v65
	v_and_b32_e32 v22, 0xffff0000, v65
	ds_bpermute_b32 v65, v26, v66
	ds_bpermute_b32 v23, v26, v22
	s_and_saveexec_b64 s[2:3], s[10:11]
	s_xor_b64 s[18:19], exec, s[2:3]
	s_cbranch_execz .LBB0_202
	s_waitcnt lgkmcnt(0)
	v_mul_f32_e32 v20, v216, v66
	v_mul_f32_e32 v21, v218, v22
	v_fmac_f32_e32 v20, v217, v65
	v_fmac_f32_e32 v21, v219, v23
.LBB0_202:
	s_andn2_saveexec_b64 s[18:19], s[18:19]
	s_cbranch_execz .LBB0_204
	s_waitcnt lgkmcnt(0)
	v_mul_f32_e32 v20, v220, v66
	v_mul_f32_e32 v21, v222, v22
	v_fma_f32 v20, -v221, v65, v20
	v_fma_f32 v21, -v223, v23, v21
.LBB0_204:
	s_or_b64 exec, exec, s[18:19]
	s_waitcnt lgkmcnt(1)
	v_add_u32_e32 v65, 1, v38
	v_cvt_f32_i32_e32 v65, v65
	s_mov_b64 s[2:3], 0xa000b80
	s_waitcnt lgkmcnt(0)
	v_lshl_add_u64 v[22:23], v[18:19], 0, s[2:3]
	v_mul_f32_e32 v66, v31, v65
	v_mul_f32_e32 v67, 0x3fb8aa3b, v66
	v_fma_f32 v68, v66, s64, -v67
	v_rndne_f32_e32 v69, v67
	v_fmac_f32_e32 v68, 0x32a5705f, v66
	v_sub_f32_e32 v67, v67, v69
	v_add_f32_e32 v67, v67, v68
	v_exp_f32_e32 v67, v67
	v_cvt_i32_f32_e32 v68, v69
	v_cmp_ngt_f32_e32 vcc, s65, v66
	v_ldexp_f32 v67, v67, v68
	s_nop 0
	v_cndmask_b32_e32 v67, 0, v67, vcc
	v_cmp_nlt_f32_e32 vcc, s89, v66
	s_nop 1
	v_cndmask_b32_e32 v66, v177, v67, vcc
	v_mul_f32_e32 v66, 0x3e000000, v66
	v_pk_mul_f32 v[20:21], v[66:67], v[20:21] op_sel_hi:[0,1]
	v_cvt_pk_bf16_f32 v20, v20, v21
	global_store_dword v[22:23], v20, off
	s_waitcnt vmcnt(29)
	v_lshlrev_b32_e32 v66, 16, v64
	v_and_b32_e32 v20, 0xffff0000, v64
	ds_bpermute_b32 v64, v26, v66
	ds_bpermute_b32 v21, v26, v20
	s_and_saveexec_b64 s[2:3], s[10:11]
	s_xor_b64 s[18:19], exec, s[2:3]
	s_cbranch_execz .LBB0_206
	s_waitcnt lgkmcnt(0)
	v_mul_f32_e32 v22, v216, v66
	v_mul_f32_e32 v23, v218, v20
	v_fmac_f32_e32 v22, v217, v64
	v_fmac_f32_e32 v23, v219, v21
.LBB0_206:
	s_andn2_saveexec_b64 s[18:19], s[18:19]
	s_cbranch_execz .LBB0_208
	s_waitcnt lgkmcnt(0)
	v_mul_f32_e32 v22, v220, v66
	v_mul_f32_e32 v23, v222, v20
	v_fma_f32 v22, -v221, v64, v22
	v_fma_f32 v23, -v223, v21, v23
.LBB0_208:
	s_or_b64 exec, exec, s[18:19]
	s_waitcnt lgkmcnt(1)
	v_mul_f32_e32 v64, v32, v65
	v_mul_f32_e32 v65, 0x3fb8aa3b, v64
	v_fma_f32 v66, v64, s64, -v65
	v_rndne_f32_e32 v67, v65
	v_fmac_f32_e32 v66, 0x32a5705f, v64
	v_sub_f32_e32 v65, v65, v67
	v_add_f32_e32 v65, v65, v66
	v_exp_f32_e32 v65, v65
	v_cvt_i32_f32_e32 v66, v67
	v_cmp_ngt_f32_e32 vcc, s65, v64
	s_mov_b64 s[2:3], 0xa000c80
	s_waitcnt lgkmcnt(0)
	v_lshl_add_u64 v[20:21], v[18:19], 0, s[2:3]
	v_ldexp_f32 v65, v65, v66
	v_cndmask_b32_e32 v65, 0, v65, vcc
	v_cmp_nlt_f32_e32 vcc, s89, v64
	s_nop 1
	v_cndmask_b32_e32 v64, v177, v65, vcc
	v_mul_f32_e32 v64, 0x3e000000, v64
	v_pk_mul_f32 v[22:23], v[64:65], v[22:23] op_sel_hi:[0,1]
	v_cvt_pk_bf16_f32 v22, v22, v23
	global_store_dword v[20:21], v22, off
	s_waitcnt vmcnt(29)
	v_lshlrev_b32_e32 v20, 16, v54
	v_and_b32_e32 v21, 0xffff0000, v54
	v_pk_mul_f32 v[22:23], v[20:21], v[20:21]
	s_nop 0
	v_add_f32_e32 v22, v22, v23
	s_nop 1
	v_add_f32_dpp v22, v22, v22 row_ror:8 row_mask:0xf bank_mask:0xf
	s_nop 1
	v_add_f32_dpp v22, v22, v22 row_ror:4 row_mask:0xf bank_mask:0xf
	s_nop 1
	v_add_f32_dpp v22, v22, v22 quad_perm:[2,3,0,1] row_mask:0xf bank_mask:0xf
	s_nop 1
	v_add_f32_dpp v22, v22, v22 quad_perm:[1,0,3,2] row_mask:0xf bank_mask:0xf
	v_fmamk_f32 v22, v22, 0x3d000000, v170
	v_cmp_gt_f32_e32 vcc, s33, v22
	v_mul_f32_e32 v23, 0x4b800000, v22
	s_nop 0
	v_cndmask_b32_e32 v22, v22, v23, vcc
	v_rsq_f32_e32 v22, v22
	s_nop 0
	v_mul_f32_e32 v23, 0x45800000, v22
	v_cndmask_b32_e32 v22, v22, v23, vcc
	v_pk_mul_f32 v[22:23], v[6:7], v[22:23] op_sel_hi:[1,0]
	s_nop 0
	v_pk_mul_f32 v[22:23], v[22:23], v[20:21]
	ds_bpermute_b32 v20, v29, v22
	ds_bpermute_b32 v21, v29, v23
	s_and_saveexec_b64 s[2:3], s[6:7]
	s_xor_b64 s[18:19], exec, s[2:3]
	s_cbranch_execz .LBB0_212
	s_and_saveexec_b64 s[30:31], s[8:9]
	s_cbranch_execz .LBB0_211
	v_add_u32_e32 v54, 0, v40
	s_waitcnt lgkmcnt(0)
	v_mul_f32_e32 v22, v22, v224
	v_mul_f32_e32 v23, v23, v226
	v_fmac_f32_e32 v22, v225, v20
	v_fmac_f32_e32 v23, v21, v227

; #define LAS __attribute__((address_space(3)))
; DI unsigned pk2(float lo, float hi) { f32x2 x = {lo, hi}; return __builtin_bit_cast(unsigned, __builtin_convertvector(x, bf16x2_t)); }
; DI float sum16(float v) { v += __shfl_xor(v, 8); v += __shfl_xor(v, 4); v += __shfl_xor(v, 2); v += __shfl_xor(v, 1); return v; }
; template <int HP> DI void rope2(f32x2& x, int hl, const LAS f32x2* cs) {
;   const float pa = __shfl_xor(x[0], HP), pb = __shfl_xor(x[1], HP);
;   if (hl < HP) { const f32x2 c0 = cs[2 * hl], c1 = cs[2 * hl + 1]; x[0] = x[0] * c0[0] - pa * c0[1]; x[1] = x[1] * c1[0] - pb * c1[1]; }
;   else if (hl < 2 * HP) { const f32x2 c0 = cs[2 * (hl - HP)], c1 = cs[2 * (hl - HP) + 1]; x[0] = x[0] * c0[0] + pa * c0[1]; x[1] = x[1] * c1[0] + pb * c1[1]; }
; DI void post_unit(const Params& p, int l, int unit, LAS unsigned char* lds) {
;     ...
;       } else {
;         const float* gn = (s < 14) ? qnc : knc;
;         const float rs = rsqrtf(sum16(x[0] * x[0] + x[1] * x[1]) * (1.0f / 32.0f) + EPS);
;         x[0] *= rs * gn[2 * hl16]; x[1] *= rs * gn[2 * hl16 + 1]; rope2<2>(x, hl16, cs8 + t * 4);
;         if (s < 14) x *= LOG2E * 0.17677669529663687f;
;         *(unsigned*)pp = pk2(x[0], x[1]);
.LBB0_212:
	s_or_saveexec_b64 s[18:19], s[18:19]
	v_add_u32_e32 v54, 0, v40
	s_xor_b64 exec, exec, s[18:19]
	s_cbranch_execz .LBB0_214
	s_waitcnt lgkmcnt(0)
	v_mul_f32_e32 v22, v22, v228
	v_mul_f32_e32 v23, v23, v230
	v_fma_f32 v22, -v229, v20, v22
	v_fma_f32 v23, -v21, v231, v23
.LBB0_214:
	s_or_b64 exec, exec, s[18:19]
	s_mov_b64 s[2:3], 0xa001180
	s_waitcnt lgkmcnt(0)
	v_lshl_add_u64 v[20:21], v[18:19], 0, s[2:3]
	s_mov_b32 s2, 0x3e8293ee
	v_pk_mul_f32 v[22:23], v[22:23], s[2:3] op_sel_hi:[1,0]
	s_nop 0
	v_cvt_pk_bf16_f32 v22, v22, v23
	global_store_dword v[20:21], v22, off
	s_waitcnt vmcnt(29)
	v_lshlrev_b32_e32 v20, 16, v63
	v_and_b32_e32 v21, 0xffff0000, v63
	v_pk_mul_f32 v[22:23], v[20:21], v[20:21]
	s_nop 0
	v_add_f32_e32 v22, v22, v23
	s_nop 1
	v_add_f32_dpp v22, v22, v22 row_ror:8 row_mask:0xf bank_mask:0xf
	s_nop 1
	v_add_f32_dpp v22, v22, v22 row_ror:4 row_mask:0xf bank_mask:0xf
	s_nop 1
	v_add_f32_dpp v22, v22, v22 quad_perm:[2,3,0,1] row_mask:0xf bank_mask:0xf
	s_nop 1
	v_add_f32_dpp v22, v22, v22 quad_perm:[1,0,3,2] row_mask:0xf bank_mask:0xf
	v_fmamk_f32 v22, v22, 0x3d000000, v170
	v_cmp_gt_f32_e32 vcc, s33, v22
	v_mul_f32_e32 v23, 0x4b800000, v22
	s_nop 0
	v_cndmask_b32_e32 v22, v22, v23, vcc
	v_rsq_f32_e32 v22, v22
	s_nop 0
	v_mul_f32_e32 v23, 0x45800000, v22
	v_cndmask_b32_e32 v22, v22, v23, vcc
	v_pk_mul_f32 v[22:23], v[6:7], v[22:23] op_sel_hi:[1,0]
	s_nop 0
	v_pk_mul_f32 v[22:23], v[22:23], v[20:21]
	ds_bpermute_b32 v20, v29, v22
	ds_bpermute_b32 v21, v29, v23
	s_and_saveexec_b64 s[2:3], s[6:7]
	s_xor_b64 s[18:19], exec, s[2:3]
	s_cbranch_execz .LBB0_218
	s_and_saveexec_b64 s[30:31], s[8:9]
	s_cbranch_execz .LBB0_217
	s_waitcnt lgkmcnt(0)
	v_mul_f32_e32 v22, v22, v224
	v_mul_f32_e32 v23, v23, v226
	v_fmac_f32_e32 v22, v225, v20
	v_fmac_f32_e32 v23, v21, v227

; #define LAS __attribute__((address_space(3)))
; DI unsigned pk2(float lo, float hi) { f32x2 x = {lo, hi}; return __builtin_bit_cast(unsigned, __builtin_convertvector(x, bf16x2_t)); }
; DI float sum16(float v) { v += __shfl_xor(v, 8); v += __shfl_xor(v, 4); v += __shfl_xor(v, 2); v += __shfl_xor(v, 1); return v; }
; template <int HP> DI void rope2(f32x2& x, int hl, const LAS f32x2* cs) {
;   const float pa = __shfl_xor(x[0], HP), pb = __shfl_xor(x[1], HP);
;   if (hl < HP) { const f32x2 c0 = cs[2 * hl], c1 = cs[2 * hl + 1]; x[0] = x[0] * c0[0] - pa * c0[1]; x[1] = x[1] * c1[0] - pb * c1[1]; }
;   else if (hl < 2 * HP) { const f32x2 c0 = cs[2 * (hl - HP)], c1 = cs[2 * (hl - HP) + 1]; x[0] = x[0] * c0[0] + pa * c0[1]; x[1] = x[1] * c1[0] + pb * c1[1]; }
; DI void post_unit(const Params& p, int l, int unit, LAS unsigned char* lds) {
;     ...
;       } else {
;         const float* gn = (s < 14) ? qnc : knc;
;         const float rs = rsqrtf(sum16(x[0] * x[0] + x[1] * x[1]) * (1.0f / 32.0f) + EPS);
;         x[0] *= rs * gn[2 * hl16]; x[1] *= rs * gn[2 * hl16 + 1]; rope2<2>(x, hl16, cs8 + t * 4);
;         if (s < 14) x *= LOG2E * 0.17677669529663687f;
;         *(unsigned*)pp = pk2(x[0], x[1]);
.LBB0_218:
	s_andn2_saveexec_b64 s[18:19], s[18:19]
	s_cbranch_execz .LBB0_220
	s_waitcnt lgkmcnt(0)
	v_mul_f32_e32 v22, v22, v228
	v_mul_f32_e32 v23, v23, v230
	v_fma_f32 v22, -v229, v20, v22
	v_fma_f32 v23, -v21, v231, v23
.LBB0_220:
	s_or_b64 exec, exec, s[18:19]
	s_mov_b64 s[2:3], 0xa001280
	s_waitcnt lgkmcnt(0)
	v_lshl_add_u64 v[20:21], v[18:19], 0, s[2:3]
	s_mov_b32 s2, 0x3e8293ee
	v_pk_mul_f32 v[22:23], v[22:23], s[2:3] op_sel_hi:[1,0]
	s_nop 0
	v_cvt_pk_bf16_f32 v22, v22, v23
	global_store_dword v[20:21], v22, off
	s_waitcnt vmcnt(29)
	v_lshlrev_b32_e32 v20, 16, v62
	v_and_b32_e32 v21, 0xffff0000, v62
	v_pk_mul_f32 v[22:23], v[20:21], v[20:21]
	s_nop 0
	v_add_f32_e32 v22, v22, v23
	s_nop 1
	v_add_f32_dpp v22, v22, v22 row_ror:8 row_mask:0xf bank_mask:0xf
	s_nop 1
	v_add_f32_dpp v22, v22, v22 row_ror:4 row_mask:0xf bank_mask:0xf
	s_nop 1
	v_add_f32_dpp v22, v22, v22 quad_perm:[2,3,0,1] row_mask:0xf bank_mask:0xf
	s_nop 1
	v_add_f32_dpp v22, v22, v22 quad_perm:[1,0,3,2] row_mask:0xf bank_mask:0xf
	v_fmamk_f32 v22, v22, 0x3d000000, v170
	v_cmp_gt_f32_e32 vcc, s33, v22
	v_mul_f32_e32 v23, 0x4b800000, v22
	s_nop 0
	v_cndmask_b32_e32 v22, v22, v23, vcc
	v_rsq_f32_e32 v22, v22
	s_nop 0
	v_mul_f32_e32 v23, 0x45800000, v22
	v_cndmask_b32_e32 v22, v22, v23, vcc
	v_pk_mul_f32 v[22:23], v[8:9], v[22:23] op_sel_hi:[1,0]
	s_nop 0
	v_pk_mul_f32 v[22:23], v[22:23], v[20:21]
	ds_bpermute_b32 v20, v29, v22
	ds_bpermute_b32 v21, v29, v23
	s_and_saveexec_b64 s[2:3], s[6:7]
	s_xor_b64 s[18:19], exec, s[2:3]
	s_cbranch_execz .LBB0_224
	s_and_saveexec_b64 s[30:31], s[8:9]
	s_cbranch_execz .LBB0_223
	s_waitcnt lgkmcnt(0)
	v_mul_f32_e32 v22, v22, v224
	v_mul_f32_e32 v23, v23, v226
	v_fmac_f32_e32 v22, v225, v20
	v_fmac_f32_e32 v23, v21, v227

; #define LAS __attribute__((address_space(3)))
; DI unsigned pk2(float lo, float hi) { f32x2 x = {lo, hi}; return __builtin_bit_cast(unsigned, __builtin_convertvector(x, bf16x2_t)); }
; DI float sum16(float v) { v += __shfl_xor(v, 8); v += __shfl_xor(v, 4); v += __shfl_xor(v, 2); v += __shfl_xor(v, 1); return v; }
; template <int HP> DI void rope2(f32x2& x, int hl, const LAS f32x2* cs) {
;   const float pa = __shfl_xor(x[0], HP), pb = __shfl_xor(x[1], HP);
;   if (hl < HP) { const f32x2 c0 = cs[2 * hl], c1 = cs[2 * hl + 1]; x[0] = x[0] * c0[0] - pa * c0[1]; x[1] = x[1] * c1[0] - pb * c1[1]; }
;   else if (hl < 2 * HP) { const f32x2 c0 = cs[2 * (hl - HP)], c1 = cs[2 * (hl - HP) + 1]; x[0] = x[0] * c0[0] + pa * c0[1]; x[1] = x[1] * c1[0] + pb * c1[1]; }
; DI void post_unit(const Params& p, int l, int unit, LAS unsigned char* lds) {
;     ...
;       } else {
;         const float* gn = (s < 14) ? qnc : knc;
;         const float rs = rsqrtf(sum16(x[0] * x[0] + x[1] * x[1]) * (1.0f / 32.0f) + EPS);
;         x[0] *= rs * gn[2 * hl16]; x[1] *= rs * gn[2 * hl16 + 1]; rope2<2>(x, hl16, cs8 + t * 4);
;         if (s < 14) x *= LOG2E * 0.17677669529663687f;
;         *(unsigned*)pp = pk2(x[0], x[1]);
.LBB0_226:
	s_or_b64 exec, exec, s[18:19]
	s_mov_b64 s[2:3], 0xa001380
	s_waitcnt lgkmcnt(0)
	v_lshl_add_u64 v[20:21], v[18:19], 0, s[2:3]
	v_cvt_pk_bf16_f32 v22, v22, v23
	global_store_dword v[20:21], v22, off
	s_waitcnt vmcnt(29)
	v_lshlrev_b32_e32 v20, 16, v61
	v_and_b32_e32 v21, 0xffff0000, v61
	v_pk_mul_f32 v[22:23], v[20:21], v[20:21]
	s_nop 0
	v_add_f32_e32 v22, v22, v23
	s_nop 1
	v_add_f32_dpp v22, v22, v22 row_ror:8 row_mask:0xf bank_mask:0xf
	s_nop 1
	v_add_f32_dpp v22, v22, v22 row_ror:4 row_mask:0xf bank_mask:0xf
	s_nop 1
	v_add_f32_dpp v22, v22, v22 quad_perm:[2,3,0,1] row_mask:0xf bank_mask:0xf
	s_nop 1
	v_add_f32_dpp v22, v22, v22 quad_perm:[1,0,3,2] row_mask:0xf bank_mask:0xf
	v_fmamk_f32 v22, v22, 0x3d000000, v170
	v_cmp_gt_f32_e32 vcc, s33, v22
	v_mul_f32_e32 v23, 0x4b800000, v22
	s_nop 0
	v_cndmask_b32_e32 v22, v22, v23, vcc
	v_rsq_f32_e32 v22, v22
	s_nop 0
	v_mul_f32_e32 v23, 0x45800000, v22
	v_cndmask_b32_e32 v22, v22, v23, vcc
	v_pk_mul_f32 v[22:23], v[8:9], v[22:23] op_sel_hi:[1,0]
	s_nop 0
	v_pk_mul_f32 v[22:23], v[22:23], v[20:21]
	ds_bpermute_b32 v20, v29, v22
	ds_bpermute_b32 v21, v29, v23
	s_and_saveexec_b64 s[2:3], s[6:7]
	s_xor_b64 s[18:19], exec, s[2:3]
	s_cbranch_execz .LBB0_230
	s_and_saveexec_b64 s[30:31], s[8:9]
	s_cbranch_execz .LBB0_229
	s_waitcnt lgkmcnt(0)
	v_mul_f32_e32 v22, v22, v224
	v_mul_f32_e32 v23, v23, v226
	v_fmac_f32_e32 v22, v225, v20
	v_fmac_f32_e32 v23, v21, v227

; #define LAS __attribute__((address_space(3)))
; DI unsigned pk2(float lo, float hi) { f32x2 x = {lo, hi}; return __builtin_bit_cast(unsigned, __builtin_convertvector(x, bf16x2_t)); }
; DI float sum32(float v) { v += __shfl_xor(v, 16); return sum16(v); }
; DI f32x2 unpk(unsigned w) { f32x2 r = {bflo(w), bfhi(w)}; return r; }
; template <int HP> DI void rope2(f32x2& x, int hl, const LAS f32x2* cs) {
;   const float pa = __shfl_xor(x[0], HP), pb = __shfl_xor(x[1], HP);
;   if (hl < HP) { const f32x2 c0 = cs[2 * hl], c1 = cs[2 * hl + 1]; x[0] = x[0] * c0[0] - pa * c0[1]; x[1] = x[1] * c1[0] - pb * c1[1]; }
;   else if (hl < 2 * HP) { const f32x2 c0 = cs[2 * (hl - HP)], c1 = cs[2 * (hl - HP) + 1]; x[0] = x[0] * c0[0] + pa * c0[1]; x[1] = x[1] * c1[0] + pb * c1[1]; }
; DI void post_unit(const Params& p, int l, int unit, LAS unsigned char* lds) {
;     ...
;       f32x2 x = unpk(raw2[hf][s]); u16* pp = row + segcol[s] + 2 * lane;
;       if (s < 2) {
;         const float rs = rsqrtf(sum32(x[0] * x[0] + x[1] * x[1]) * (1.0f / 64.0f) + EPS);
;         x[0] *= rs * qna[2 * hl]; x[1] *= rs * qna[2 * hl + 1]; rope2<4>(x, hl, cs16 + t * 8);
;         x *= LOG2E * 0.125f; *(unsigned*)pp = pk2(x[0], x[1]);
.LBB0_232:
	s_or_b64 exec, exec, s[18:19]
	s_mov_b64 s[2:3], 0xa001480
	v_lshl_add_u64 v[18:19], v[18:19], 0, s[2:3]
	s_waitcnt lgkmcnt(1)
	v_cvt_pk_bf16_f32 v20, v22, v23
	global_store_dword v[18:19], v20, off
	s_waitcnt vmcnt(29)
	v_and_b32_e32 v19, 0xffff0000, v60
	v_lshlrev_b32_e32 v18, 16, v60
	s_waitcnt lgkmcnt(0)
	v_pk_mul_f32 v[20:21], v[18:19], v[18:19]
	s_nop 0
	v_add_f32_e32 v20, v20, v21
	v_mov_b32_e32 v21, v20
	s_nop 1
	v_permlane16_swap_b32_e32 v20, v21
	v_add_f32_e32 v20, v20, v21
	s_nop 1
	v_add_f32_dpp v20, v20, v20 row_ror:8 row_mask:0xf bank_mask:0xf
	s_nop 1
	v_add_f32_dpp v20, v20, v20 row_ror:4 row_mask:0xf bank_mask:0xf
	s_nop 1
	v_add_f32_dpp v20, v20, v20 quad_perm:[2,3,0,1] row_mask:0xf bank_mask:0xf
	s_nop 1
	v_add_f32_dpp v20, v20, v20 quad_perm:[1,0,3,2] row_mask:0xf bank_mask:0xf
	v_fmamk_f32 v20, v20, 0x3c800000, v170
	v_cmp_gt_f32_e32 vcc, s33, v20
	v_mul_f32_e32 v21, 0x4b800000, v20
	s_nop 0
	v_cndmask_b32_e32 v20, v20, v21, vcc
	v_rsq_f32_e32 v20, v20
	s_nop 0
	v_mul_f32_e32 v21, 0x45800000, v20
	v_cndmask_b32_e32 v20, v20, v21, vcc
	v_pk_mul_f32 v[20:21], v[4:5], v[20:21] op_sel_hi:[1,0]
	s_nop 0
	v_pk_mul_f32 v[20:21], v[20:21], v[18:19]
	ds_bpermute_b32 v18, v28, v20
	ds_bpermute_b32 v19, v28, v21
	s_and_saveexec_b64 s[2:3], s[12:13]
	s_xor_b64 s[18:19], exec, s[2:3]
	s_cbranch_execz .LBB0_236
	s_and_saveexec_b64 s[30:31], s[14:15]
	s_cbranch_execz .LBB0_235
	s_waitcnt lgkmcnt(0)
	v_mul_f32_e32 v20, v20, v212
	v_mul_f32_e32 v21, v21, v214
	v_fmac_f32_e32 v20, v213, v18
	v_fmac_f32_e32 v21, v19, v215

; #define LAS __attribute__((address_space(3)))
; DI unsigned pk2(float lo, float hi) { f32x2 x = {lo, hi}; return __builtin_bit_cast(unsigned, __builtin_convertvector(x, bf16x2_t)); }
; DI float sum32(float v) { v += __shfl_xor(v, 16); return sum16(v); }
; DI f32x2 unpk(unsigned w) { f32x2 r = {bflo(w), bfhi(w)}; return r; }
; template <int HP> DI void rope2(f32x2& x, int hl, const LAS f32x2* cs) {
;   const float pa = __shfl_xor(x[0], HP), pb = __shfl_xor(x[1], HP);
;   if (hl < HP) { const f32x2 c0 = cs[2 * hl], c1 = cs[2 * hl + 1]; x[0] = x[0] * c0[0] - pa * c0[1]; x[1] = x[1] * c1[0] - pb * c1[1]; }
;   else if (hl < 2 * HP) { const f32x2 c0 = cs[2 * (hl - HP)], c1 = cs[2 * (hl - HP) + 1]; x[0] = x[0] * c0[0] + pa * c0[1]; x[1] = x[1] * c1[0] + pb * c1[1]; }
; DI void post_unit(const Params& p, int l, int unit, LAS unsigned char* lds) {
;     ...
;       f32x2 x = unpk(raw2[hf][s]); u16* pp = row + segcol[s] + 2 * lane;
;       if (s < 2) {
;         const float rs = rsqrtf(sum32(x[0] * x[0] + x[1] * x[1]) * (1.0f / 64.0f) + EPS);
;         x[0] *= rs * qna[2 * hl]; x[1] *= rs * qna[2 * hl + 1]; rope2<4>(x, hl, cs16 + t * 8);
;         x *= LOG2E * 0.125f; *(unsigned*)pp = pk2(x[0], x[1]);
.LBB0_236:
	s_andn2_saveexec_b64 s[18:19], s[18:19]
	s_cbranch_execz .LBB0_238
	s_waitcnt lgkmcnt(0)
	v_mul_f32_e32 v20, v20, v232
	v_mul_f32_e32 v21, v21, v234
	v_fma_f32 v20, -v233, v18, v20
	v_fma_f32 v21, -v19, v235, v21
.LBB0_238:
	s_or_b64 exec, exec, s[18:19]
	s_mov_b32 s2, 0x3e38aa3b
	s_waitcnt lgkmcnt(0)
	v_lshl_add_u64 v[18:19], v[14:15], 0, v[0:1]
	v_pk_mul_f32 v[20:21], v[20:21], s[2:3] op_sel_hi:[1,0]
	s_nop 0
	v_cvt_pk_bf16_f32 v22, v20, v21
	v_add_co_u32_e32 v20, vcc, 0xa002000, v18
	s_nop 1
	v_addc_co_u32_e32 v21, vcc, 0, v19, vcc
	global_store_dword v[20:21], v22, off offset:512
	s_waitcnt vmcnt(29)
	v_and_b32_e32 v21, 0xffff0000, v57
	v_lshlrev_b32_e32 v20, 16, v57
	v_pk_mul_f32 v[22:23], v[20:21], v[20:21]
	s_nop 0
	v_add_f32_e32 v22, v22, v23
	v_mov_b32_e32 v23, v22
	s_nop 1
	v_permlane16_swap_b32_e32 v22, v23
	v_add_f32_e32 v22, v22, v23
	s_nop 1
	v_add_f32_dpp v22, v22, v22 row_ror:8 row_mask:0xf bank_mask:0xf
	s_nop 1
	v_add_f32_dpp v22, v22, v22 row_ror:4 row_mask:0xf bank_mask:0xf
	s_nop 1
	v_add_f32_dpp v22, v22, v22 quad_perm:[2,3,0,1] row_mask:0xf bank_mask:0xf
	s_nop 1
	v_add_f32_dpp v22, v22, v22 quad_perm:[1,0,3,2] row_mask:0xf bank_mask:0xf
	v_fmamk_f32 v22, v22, 0x3c800000, v170
	v_cmp_gt_f32_e32 vcc, s33, v22
	v_mul_f32_e32 v23, 0x4b800000, v22
	s_nop 0
	v_cndmask_b32_e32 v22, v22, v23, vcc
	v_rsq_f32_e32 v22, v22
	s_nop 0
	v_mul_f32_e32 v23, 0x45800000, v22
	v_cndmask_b32_e32 v22, v22, v23, vcc
	v_pk_mul_f32 v[22:23], v[4:5], v[22:23] op_sel_hi:[1,0]
	s_nop 0
	v_pk_mul_f32 v[22:23], v[22:23], v[20:21]
	ds_bpermute_b32 v20, v28, v22
	ds_bpermute_b32 v21, v28, v23
	s_and_saveexec_b64 s[2:3], s[12:13]
	s_xor_b64 s[18:19], exec, s[2:3]
	s_cbranch_execz .LBB0_242
	s_and_saveexec_b64 s[30:31], s[14:15]
	s_cbranch_execz .LBB0_241
	s_waitcnt lgkmcnt(0)
	v_mul_f32_e32 v22, v22, v212
	v_mul_f32_e32 v23, v23, v214
	v_fmac_f32_e32 v22, v213, v20
	v_fmac_f32_e32 v23, v21, v215

; #define LAS __attribute__((address_space(3)))
; DI unsigned pk2(float lo, float hi) { f32x2 x = {lo, hi}; return __builtin_bit_cast(unsigned, __builtin_convertvector(x, bf16x2_t)); }
; DI float sum32(float v) { v += __shfl_xor(v, 16); return sum16(v); }
; DI float sum64(float v) { v += __shfl_xor(v, 32); return sum32(v); }
; DI f32x2 unpk(unsigned w) { f32x2 r = {bflo(w), bfhi(w)}; return r; }
; template <int HP> DI void rope2(f32x2& x, int hl, const LAS f32x2* cs) {
;   const float pa = __shfl_xor(x[0], HP), pb = __shfl_xor(x[1], HP);
;   if (hl < HP) { const f32x2 c0 = cs[2 * hl], c1 = cs[2 * hl + 1]; x[0] = x[0] * c0[0] - pa * c0[1]; x[1] = x[1] * c1[0] - pb * c1[1]; }
;   else if (hl < 2 * HP) { const f32x2 c0 = cs[2 * (hl - HP)], c1 = cs[2 * (hl - HP) + 1]; x[0] = x[0] * c0[0] + pa * c0[1]; x[1] = x[1] * c1[0] + pb * c1[1]; }
; DI void post_unit(const Params& p, int l, int unit, LAS unsigned char* lds) {
;     ...
;       f32x2 x = unpk(raw2[hf][s]); u16* pp = row + segcol[s] + 2 * lane;
;       if (s < 2) {
;         const float rs = rsqrtf(sum32(x[0] * x[0] + x[1] * x[1]) * (1.0f / 64.0f) + EPS);
;         x[0] *= rs * qna[2 * hl]; x[1] *= rs * qna[2 * hl + 1]; rope2<4>(x, hl, cs16 + t * 8);
;         x *= LOG2E * 0.125f; *(unsigned*)pp = pk2(x[0], x[1]);
;       } else if (s == 2) {
;         const float rs = rsqrtf(sum64(x[0] * x[0] + x[1] * x[1]) * (1.0f / 128.0f) + EPS);
;         *(LAS unsigned*)(At + t * 272 + lane * 4) = pk2(x[0] * rs, x[1] * rs);
;       } else if (s < 7) {
;         rope2<4>(x, hl, cs16 + t * 8); *(unsigned*)pp = pk2(x[0], x[1]);
.LBB0_242:
	s_andn2_saveexec_b64 s[18:19], s[18:19]
	s_cbranch_execz .LBB0_244
	s_waitcnt lgkmcnt(0)
	v_mul_f32_e32 v22, v22, v232
	v_mul_f32_e32 v23, v23, v234
	v_fma_f32 v22, -v233, v20, v22
	v_fma_f32 v23, -v21, v235, v23
.LBB0_244:
	s_or_b64 exec, exec, s[18:19]
	s_mov_b32 s2, 0x3e38aa3b
	s_waitcnt lgkmcnt(0)
	v_pk_mul_f32 v[20:21], v[22:23], s[2:3] op_sel_hi:[1,0]
	s_nop 0
	v_cvt_pk_bf16_f32 v22, v20, v21
	v_add_co_u32_e32 v20, vcc, 0xa002000, v18
	s_nop 1
	v_addc_co_u32_e32 v21, vcc, 0, v19, vcc
	global_store_dword v[20:21], v22, off offset:768
	s_waitcnt vmcnt(29)
	v_lshlrev_b32_e32 v20, 16, v55
	v_and_b32_e32 v21, 0xffff0000, v55
	v_pk_mul_f32 v[22:23], v[20:21], v[20:21]
	s_nop 0
	v_add_f32_e32 v22, v22, v23
	v_mov_b32_e32 v23, v22
	s_nop 1
	v_permlane32_swap_b32_e32 v22, v23
	v_add_f32_e32 v22, v22, v23
	v_mov_b32_e32 v23, v22
	s_nop 1
	v_permlane16_swap_b32_e32 v22, v23
	v_add_f32_e32 v22, v22, v23
	s_nop 1
	v_add_f32_dpp v22, v22, v22 row_ror:8 row_mask:0xf bank_mask:0xf
	s_nop 1
	v_add_f32_dpp v22, v22, v22 row_ror:4 row_mask:0xf bank_mask:0xf
	s_nop 1
	v_add_f32_dpp v22, v22, v22 quad_perm:[2,3,0,1] row_mask:0xf bank_mask:0xf
	s_nop 1
	v_add_f32_dpp v22, v22, v22 quad_perm:[1,0,3,2] row_mask:0xf bank_mask:0xf
	v_fmamk_f32 v22, v22, 0x3c000000, v170
	v_cmp_gt_f32_e32 vcc, s33, v22
	v_mul_f32_e32 v23, 0x4b800000, v22
	s_nop 0
	v_cndmask_b32_e32 v22, v22, v23, vcc
	v_rsq_f32_e32 v22, v22
	s_nop 0
	v_mul_f32_e32 v23, 0x45800000, v22
	v_cndmask_b32_e32 v22, v22, v23, vcc
	v_pk_mul_f32 v[20:21], v[22:23], v[20:21] op_sel_hi:[0,1]
	v_cvt_pk_bf16_f32 v20, v20, v21
	ds_write_b32 v59, v20 offset:272
	s_waitcnt vmcnt(28)
	v_lshlrev_b32_e32 v20, 16, v53
	v_and_b32_e32 v21, 0xffff0000, v53
	ds_bpermute_b32 v53, v28, v20
	ds_bpermute_b32 v23, v28, v21
	s_and_saveexec_b64 s[2:3], s[12:13]
	s_xor_b64 s[18:19], exec, s[2:3]
	s_cbranch_execz .LBB0_248
	s_and_saveexec_b64 s[30:31], s[14:15]
	s_cbranch_execz .LBB0_247
	v_mov_b32_e32 v22, v21
	s_waitcnt lgkmcnt(0)
	v_mul_f32_e32 v20, v212, v20
	v_mul_f32_e32 v21, v214, v22
	v_fmac_f32_e32 v20, v213, v53
	v_fmac_f32_e32 v21, v215, v23

; #define LAS __attribute__((address_space(3)))
; DI unsigned pk2(float lo, float hi) { f32x2 x = {lo, hi}; return __builtin_bit_cast(unsigned, __builtin_convertvector(x, bf16x2_t)); }
; template <int HP> DI void rope2(f32x2& x, int hl, const LAS f32x2* cs) {
;   const float pa = __shfl_xor(x[0], HP), pb = __shfl_xor(x[1], HP);
;   if (hl < HP) { const f32x2 c0 = cs[2 * hl], c1 = cs[2 * hl + 1]; x[0] = x[0] * c0[0] - pa * c0[1]; x[1] = x[1] * c1[0] - pb * c1[1]; }
;   else if (hl < 2 * HP) { const f32x2 c0 = cs[2 * (hl - HP)], c1 = cs[2 * (hl - HP) + 1]; x[0] = x[0] * c0[0] + pa * c0[1]; x[1] = x[1] * c1[0] + pb * c1[1]; }
; DI void post_unit(const Params& p, int l, int unit, LAS unsigned char* lds) {
;     ...
;       } else if (s < 7) {
;         rope2<4>(x, hl, cs16 + t * 8); *(unsigned*)pp = pk2(x[0], x[1]);
.LBB0_248:
	s_andn2_saveexec_b64 s[18:19], s[18:19]
	s_cbranch_execz .LBB0_250
	v_mov_b32_e32 v22, v21
	s_waitcnt lgkmcnt(0)
	v_mul_f32_e32 v20, v232, v20
	v_mul_f32_e32 v21, v234, v22
	v_fma_f32 v20, -v233, v53, v20
	v_fma_f32 v21, -v235, v23, v21
.LBB0_250:
	s_or_b64 exec, exec, s[18:19]
	v_cvt_pk_bf16_f32 v22, v20, v21
	v_add_co_u32_e32 v20, vcc, 0xa002000, v18
	s_nop 1
	v_addc_co_u32_e32 v21, vcc, 0, v19, vcc
	global_store_dword v[20:21], v22, off offset:1280
	s_waitcnt vmcnt(28)
	v_lshlrev_b32_e32 v20, 16, v52
	v_and_b32_e32 v21, 0xffff0000, v52
	ds_bpermute_b32 v52, v28, v20
	s_waitcnt lgkmcnt(1)
	ds_bpermute_b32 v23, v28, v21
	s_and_saveexec_b64 s[2:3], s[12:13]
	s_xor_b64 s[18:19], exec, s[2:3]
	s_cbranch_execz .LBB0_254
	s_and_saveexec_b64 s[30:31], s[14:15]
	s_cbranch_execz .LBB0_253
	v_mov_b32_e32 v22, v21
	s_waitcnt lgkmcnt(0)
	v_mul_f32_e32 v20, v212, v20
	v_mul_f32_e32 v21, v214, v22
	v_fmac_f32_e32 v20, v213, v52
	v_fmac_f32_e32 v21, v215, v23

; #define LAS __attribute__((address_space(3)))
; DI unsigned pk2(float lo, float hi) { f32x2 x = {lo, hi}; return __builtin_bit_cast(unsigned, __builtin_convertvector(x, bf16x2_t)); }
; template <int HP> DI void rope2(f32x2& x, int hl, const LAS f32x2* cs) {
;   const float pa = __shfl_xor(x[0], HP), pb = __shfl_xor(x[1], HP);
;   if (hl < HP) { const f32x2 c0 = cs[2 * hl], c1 = cs[2 * hl + 1]; x[0] = x[0] * c0[0] - pa * c0[1]; x[1] = x[1] * c1[0] - pb * c1[1]; }
;   else if (hl < 2 * HP) { const f32x2 c0 = cs[2 * (hl - HP)], c1 = cs[2 * (hl - HP) + 1]; x[0] = x[0] * c0[0] + pa * c0[1]; x[1] = x[1] * c1[0] + pb * c1[1]; }
; }
; DI void post_unit(const Params& p, int l, int unit, LAS unsigned char* lds) {
;     ...
;       } else if (s < 7) {
;         rope2<4>(x, hl, cs16 + t * 8); *(unsigned*)pp = pk2(x[0], x[1]);
.LBB0_254:
	s_andn2_saveexec_b64 s[18:19], s[18:19]
	s_cbranch_execz .LBB0_256
	v_mov_b32_e32 v22, v21
	s_waitcnt lgkmcnt(0)
	v_mul_f32_e32 v20, v232, v20
	v_mul_f32_e32 v21, v234, v22
	v_fma_f32 v20, -v233, v52, v20
	v_fma_f32 v21, -v235, v23, v21
.LBB0_256:
	s_or_b64 exec, exec, s[18:19]
	v_cvt_pk_bf16_f32 v22, v20, v21
	v_add_co_u32_e32 v20, vcc, 0xa002000, v18
	s_nop 1
	v_addc_co_u32_e32 v21, vcc, 0, v19, vcc
	global_store_dword v[20:21], v22, off offset:1536
	s_waitcnt vmcnt(28)
	v_lshlrev_b32_e32 v20, 16, v51
	v_and_b32_e32 v21, 0xffff0000, v51
	ds_bpermute_b32 v51, v28, v20
	s_waitcnt lgkmcnt(1)
	ds_bpermute_b32 v23, v28, v21
	s_and_saveexec_b64 s[2:3], s[12:13]
	s_xor_b64 s[18:19], exec, s[2:3]
	s_cbranch_execz .LBB0_260
	s_and_saveexec_b64 s[30:31], s[14:15]
	s_cbranch_execz .LBB0_259
	v_mov_b32_e32 v22, v21
	s_waitcnt lgkmcnt(0)
	v_mul_f32_e32 v20, v212, v20
	v_mul_f32_e32 v21, v214, v22
	v_fmac_f32_e32 v20, v213, v51
	v_fmac_f32_e32 v21, v215, v23

; #define LAS __attribute__((address_space(3)))
; DI unsigned pk2(float lo, float hi) { f32x2 x = {lo, hi}; return __builtin_bit_cast(unsigned, __builtin_convertvector(x, bf16x2_t)); }
; template <int HP> DI void rope2(f32x2& x, int hl, const LAS f32x2* cs) {
;   const float pa = __shfl_xor(x[0], HP), pb = __shfl_xor(x[1], HP);
;   if (hl < HP) { const f32x2 c0 = cs[2 * hl], c1 = cs[2 * hl + 1]; x[0] = x[0] * c0[0] - pa * c0[1]; x[1] = x[1] * c1[0] - pb * c1[1]; }
;   else if (hl < 2 * HP) { const f32x2 c0 = cs[2 * (hl - HP)], c1 = cs[2 * (hl - HP) + 1]; x[0] = x[0] * c0[0] + pa * c0[1]; x[1] = x[1] * c1[0] + pb * c1[1]; }
; }
; DI void post_unit(const Params& p, int l, int unit, LAS unsigned char* lds) {
;     ...
;       } else if (s < 7) {
;         rope2<4>(x, hl, cs16 + t * 8); *(unsigned*)pp = pk2(x[0], x[1]);
.LBB0_260:
	s_andn2_saveexec_b64 s[18:19], s[18:19]
	s_cbranch_execz .LBB0_262
	v_mov_b32_e32 v22, v21
	s_waitcnt lgkmcnt(0)
	v_mul_f32_e32 v20, v232, v20
	v_mul_f32_e32 v21, v234, v22
	v_fma_f32 v20, -v233, v51, v20
	v_fma_f32 v21, -v235, v23, v21
.LBB0_262:
	s_or_b64 exec, exec, s[18:19]
	v_cvt_pk_bf16_f32 v22, v20, v21
	v_add_co_u32_e32 v20, vcc, 0xa002000, v18
	s_nop 1
	v_addc_co_u32_e32 v21, vcc, 0, v19, vcc
	global_store_dword v[20:21], v22, off offset:1792
	s_waitcnt vmcnt(28)
	v_lshlrev_b32_e32 v20, 16, v50
	v_and_b32_e32 v21, 0xffff0000, v50
	ds_bpermute_b32 v50, v28, v20
	s_waitcnt lgkmcnt(1)
	ds_bpermute_b32 v23, v28, v21
	s_and_saveexec_b64 s[2:3], s[12:13]
	s_xor_b64 s[18:19], exec, s[2:3]
	s_cbranch_execz .LBB0_266
	s_and_saveexec_b64 s[30:31], s[14:15]
	s_cbranch_execz .LBB0_265
	v_mov_b32_e32 v22, v21
	s_waitcnt lgkmcnt(0)
	v_mul_f32_e32 v20, v212, v20
	v_mul_f32_e32 v21, v214, v22
	v_fmac_f32_e32 v20, v213, v50
	v_fmac_f32_e32 v21, v215, v23

; #define LAS __attribute__((address_space(3)))
; DI unsigned pk2(float lo, float hi) { f32x2 x = {lo, hi}; return __builtin_bit_cast(unsigned, __builtin_convertvector(x, bf16x2_t)); }
; DI float sum32(float v) { v += __shfl_xor(v, 16); return sum16(v); }
; template <int HP> DI void rope2(f32x2& x, int hl, const LAS f32x2* cs) {
;   const float pa = __shfl_xor(x[0], HP), pb = __shfl_xor(x[1], HP);
;   if (hl < HP) { const f32x2 c0 = cs[2 * hl], c1 = cs[2 * hl + 1]; x[0] = x[0] * c0[0] - pa * c0[1]; x[1] = x[1] * c1[0] - pb * c1[1]; }
;   else if (hl < 2 * HP) { const f32x2 c0 = cs[2 * (hl - HP)], c1 = cs[2 * (hl - HP) + 1]; x[0] = x[0] * c0[0] + pa * c0[1]; x[1] = x[1] * c1[0] + pb * c1[1]; }
; }
; DI void post_unit(const Params& p, int l, int unit, LAS unsigned char* lds) {
;     ...
;       } else if (s < 7) {
;         rope2<4>(x, hl, cs16 + t * 8); *(unsigned*)pp = pk2(x[0], x[1]);
;       } else if (s == 7) {
;         const float rs = rsqrtf(sum32(x[0] * x[0] + x[1] * x[1]) * (1.0f / 64.0f) + EPS);
;         x *= rs; rope2<4>(x, hl, cs16 + t * 8); if (lane < 32) *(unsigned*)((u16*)(p.ws + WS_KIC) + (tok0 + t) * 64 + 2 * lane) = pk2(x[0], x[1]);
.LBB0_266:
	s_andn2_saveexec_b64 s[18:19], s[18:19]
	s_cbranch_execz .LBB0_268
	v_mov_b32_e32 v22, v21
	s_waitcnt lgkmcnt(0)
	v_mul_f32_e32 v20, v232, v20
	v_mul_f32_e32 v21, v234, v22
	v_fma_f32 v20, -v233, v50, v20
	v_fma_f32 v21, -v235, v23, v21
.LBB0_268:
	s_or_b64 exec, exec, s[18:19]
	v_cvt_pk_bf16_f32 v22, v20, v21
	v_add_co_u32_e32 v20, vcc, 0xa002000, v18
	s_nop 1
	v_addc_co_u32_e32 v21, vcc, 0, v19, vcc
	global_store_dword v[20:21], v22, off offset:2048
	s_waitcnt vmcnt(28)
	v_lshlrev_b32_e32 v20, 16, v48
	v_and_b32_e32 v21, 0xffff0000, v48
	s_waitcnt lgkmcnt(0)
	v_pk_mul_f32 v[22:23], v[20:21], v[20:21]
	s_nop 0
	v_add_f32_e32 v22, v22, v23
	v_mov_b32_e32 v23, v22
	s_nop 1
	v_permlane16_swap_b32_e32 v22, v23
	v_add_f32_e32 v22, v22, v23
	s_nop 1
	v_add_f32_dpp v22, v22, v22 row_ror:8 row_mask:0xf bank_mask:0xf
	s_nop 1
	v_add_f32_dpp v22, v22, v22 row_ror:4 row_mask:0xf bank_mask:0xf
	s_nop 1
	v_add_f32_dpp v22, v22, v22 quad_perm:[2,3,0,1] row_mask:0xf bank_mask:0xf
	s_nop 1
	v_add_f32_dpp v22, v22, v22 quad_perm:[1,0,3,2] row_mask:0xf bank_mask:0xf
	v_fmamk_f32 v22, v22, 0x3c800000, v170
	v_cmp_gt_f32_e32 vcc, s33, v22
	v_mul_f32_e32 v23, 0x4b800000, v22
	s_nop 0
	v_cndmask_b32_e32 v22, v22, v23, vcc
	v_rsq_f32_e32 v22, v22
	s_nop 0
	v_mul_f32_e32 v23, 0x45800000, v22
	v_cndmask_b32_e32 v22, v22, v23, vcc
	v_pk_mul_f32 v[20:21], v[22:23], v[20:21] op_sel_hi:[0,1]
	ds_bpermute_b32 v22, v28, v20
	ds_bpermute_b32 v23, v28, v21
	s_and_saveexec_b64 s[2:3], s[12:13]
	s_xor_b64 s[18:19], exec, s[2:3]
	s_cbranch_execz .LBB0_316
	s_and_saveexec_b64 s[30:31], s[14:15]
	s_cbranch_execz .LBB0_271
	s_waitcnt lgkmcnt(0)
	v_mul_f32_e32 v20, v20, v212
	v_mul_f32_e32 v21, v214, v21
	v_fmac_f32_e32 v20, v213, v22
	v_fmac_f32_e32 v21, v215, v23

; #define LAS __attribute__((address_space(3)))
; DI unsigned pk2(float lo, float hi) { f32x2 x = {lo, hi}; return __builtin_bit_cast(unsigned, __builtin_convertvector(x, bf16x2_t)); }
; template <int HP> DI void rope2(f32x2& x, int hl, const LAS f32x2* cs) {
;   const float pa = __shfl_xor(x[0], HP), pb = __shfl_xor(x[1], HP);
;   if (hl < HP) { const f32x2 c0 = cs[2 * hl], c1 = cs[2 * hl + 1]; x[0] = x[0] * c0[0] - pa * c0[1]; x[1] = x[1] * c1[0] - pb * c1[1]; }
;   else if (hl < 2 * HP) { const f32x2 c0 = cs[2 * (hl - HP)], c1 = cs[2 * (hl - HP) + 1]; x[0] = x[0] * c0[0] + pa * c0[1]; x[1] = x[1] * c1[0] + pb * c1[1]; }
; }
; DI void post_unit(const Params& p, int l, int unit, LAS unsigned char* lds) {
;     ...
;       } else if (s < 12) {
;         rope2<16>(x, hl, cs64 + t * 32);
;         const int hd = ((s & 1) ? 2 : 0) + hsel;
;         const float lg = log1pf(-exp2f(-5.0f - (float)hd));
;         const float f = (s < 10) ? expf(lg * (float)(t + 1)) : expf(lg * (float)(63 - t)) * 0.125f;
;         x *= f; *(unsigned*)pp = pk2(x[0], x[1]);
.LBB0_274:
	s_or_b64 exec, exec, s[18:19]
	s_waitcnt vmcnt(27)
	v_lshlrev_b32_e32 v48, 16, v47
	s_waitcnt lgkmcnt(1)
	v_and_b32_e32 v22, 0xffff0000, v47
	ds_bpermute_b32 v47, v26, v48
	s_waitcnt lgkmcnt(1)
	ds_bpermute_b32 v23, v26, v22
	s_and_saveexec_b64 s[2:3], s[10:11]
	s_xor_b64 s[18:19], exec, s[2:3]
	s_cbranch_execz .LBB0_276
	s_waitcnt lgkmcnt(0)
	v_mul_f32_e32 v20, v220, v48
	v_mul_f32_e32 v21, v222, v22
	v_fmac_f32_e32 v20, v221, v47
	v_fmac_f32_e32 v21, v223, v23
.LBB0_276:
	s_andn2_saveexec_b64 s[18:19], s[18:19]
	s_cbranch_execz .LBB0_278
	s_waitcnt lgkmcnt(0)
	v_mul_f32_e32 v20, v236, v48
	v_mul_f32_e32 v21, v238, v22
	v_fma_f32 v20, -v237, v47, v20
	v_fma_f32 v21, -v239, v23, v21
.LBB0_278:
	s_or_b64 exec, exec, s[18:19]
	v_add_u32_e32 v22, 2, v58
	s_waitcnt lgkmcnt(1)
	v_cvt_f32_i32_e32 v47, v22
	v_mul_f32_e32 v22, v31, v47
	s_waitcnt lgkmcnt(0)
	v_mul_f32_e32 v23, 0x3fb8aa3b, v22
	v_fma_f32 v48, v22, s64, -v23
	v_rndne_f32_e32 v49, v23
	v_fmac_f32_e32 v48, 0x32a5705f, v22
	v_sub_f32_e32 v23, v23, v49
	v_add_f32_e32 v23, v23, v48
	v_cvt_i32_f32_e32 v49, v49
	v_exp_f32_e32 v23, v23
	v_cmp_ngt_f32_e32 vcc, s65, v22
	s_waitcnt vmcnt(26)
	v_lshlrev_b32_e32 v48, 16, v46
	v_ldexp_f32 v23, v23, v49
	v_cndmask_b32_e32 v23, 0, v23, vcc
	v_cmp_nlt_f32_e32 vcc, s89, v22
	s_nop 1
	v_cndmask_b32_e32 v22, v177, v23, vcc
	v_pk_mul_f32 v[20:21], v[22:23], v[20:21] op_sel_hi:[0,1]
	v_and_b32_e32 v22, 0xffff0000, v46
	ds_bpermute_b32 v46, v26, v48
	ds_bpermute_b32 v23, v26, v22
	v_cvt_pk_bf16_f32 v49, v20, v21
	v_add_co_u32_e32 v20, vcc, 0xa002000, v18
	s_nop 1
	v_addc_co_u32_e32 v21, vcc, 0, v19, vcc
	global_store_dword v[20:21], v49, off offset:2944
	s_and_saveexec_b64 s[2:3], s[10:11]
	s_xor_b64 s[18:19], exec, s[2:3]
	s_cbranch_execz .LBB0_280
	s_waitcnt lgkmcnt(0)
	v_mul_f32_e32 v20, v220, v48
	v_mul_f32_e32 v21, v222, v22
	v_fmac_f32_e32 v20, v221, v46
	v_fmac_f32_e32 v21, v223, v23
.LBB0_280:
	s_andn2_saveexec_b64 s[18:19], s[18:19]
	s_cbranch_execz .LBB0_282
	s_waitcnt lgkmcnt(0)
	v_mul_f32_e32 v20, v236, v48
	v_mul_f32_e32 v21, v238, v22
	v_fma_f32 v20, -v237, v46, v20
	v_fma_f32 v21, -v239, v23, v21
.LBB0_282:
	s_or_b64 exec, exec, s[18:19]
	v_mul_f32_e32 v22, v32, v47
	s_waitcnt lgkmcnt(0)
	v_mul_f32_e32 v23, 0x3fb8aa3b, v22
	v_fma_f32 v46, v22, s64, -v23
	v_rndne_f32_e32 v47, v23
	v_fmac_f32_e32 v46, 0x32a5705f, v22
	v_sub_f32_e32 v23, v23, v47
	v_add_f32_e32 v23, v23, v46
	v_cvt_i32_f32_e32 v46, v47
	v_exp_f32_e32 v23, v23
	v_cmp_ngt_f32_e32 vcc, s65, v22
	v_ldexp_f32 v23, v23, v46
	s_nop 0
	v_cndmask_b32_e32 v23, 0, v23, vcc
	v_cmp_nlt_f32_e32 vcc, s89, v22
	s_waitcnt vmcnt(26)
	v_lshlrev_b32_e32 v46, 16, v45
	v_cndmask_b32_e32 v22, v177, v23, vcc
	v_pk_mul_f32 v[20:21], v[22:23], v[20:21] op_sel_hi:[0,1]
	v_and_b32_e32 v22, 0xffff0000, v45
	ds_bpermute_b32 v45, v26, v46
	ds_bpermute_b32 v23, v26, v22
	v_cvt_pk_bf16_f32 v47, v20, v21
	v_add_co_u32_e32 v20, vcc, 0xa002000, v18
	s_nop 1
	v_addc_co_u32_e32 v21, vcc, 0, v19, vcc
	global_store_dword v[20:21], v47, off offset:3200
	s_and_saveexec_b64 s[2:3], s[10:11]
	s_xor_b64 s[18:19], exec, s[2:3]
	s_cbranch_execz .LBB0_284
	s_waitcnt lgkmcnt(0)
	v_mul_f32_e32 v20, v220, v46
	v_mul_f32_e32 v21, v222, v22
	v_fmac_f32_e32 v20, v221, v45
	v_fmac_f32_e32 v21, v223, v23
.LBB0_284:
	s_andn2_saveexec_b64 s[18:19], s[18:19]
	s_cbranch_execz .LBB0_286
	s_waitcnt lgkmcnt(0)
	v_mul_f32_e32 v20, v236, v46
	v_mul_f32_e32 v21, v238, v22
	v_fma_f32 v20, -v237, v45, v20
	v_fma_f32 v21, -v239, v23, v21
.LBB0_286:
	s_or_b64 exec, exec, s[18:19]
	s_waitcnt lgkmcnt(1)
	v_cvt_f32_i32_e32 v45, v38
	v_mul_f32_e32 v22, v31, v45
	s_waitcnt lgkmcnt(0)
	v_mul_f32_e32 v23, 0x3fb8aa3b, v22
	v_fma_f32 v46, v22, s64, -v23
	v_rndne_f32_e32 v47, v23
	v_fmac_f32_e32 v46, 0x32a5705f, v22
	v_sub_f32_e32 v23, v23, v47
	v_add_f32_e32 v23, v23, v46
	v_cvt_i32_f32_e32 v47, v47
	v_exp_f32_e32 v23, v23
	v_cmp_ngt_f32_e32 vcc, s65, v22
	s_waitcnt vmcnt(26)
	v_lshlrev_b32_e32 v46, 16, v44
	v_ldexp_f32 v23, v23, v47
	v_cndmask_b32_e32 v23, 0, v23, vcc
	v_cmp_nlt_f32_e32 vcc, s89, v22
	s_nop 1
	v_cndmask_b32_e32 v22, v177, v23, vcc
	v_mul_f32_e32 v22, 0x3e000000, v22
	v_pk_mul_f32 v[20:21], v[22:23], v[20:21] op_sel_hi:[0,1]
	v_and_b32_e32 v22, 0xffff0000, v44
	ds_bpermute_b32 v44, v26, v46
	ds_bpermute_b32 v23, v26, v22
	v_cvt_pk_bf16_f32 v47, v20, v21
	v_add_co_u32_e32 v20, vcc, 0xa002000, v18
	s_nop 1
	v_addc_co_u32_e32 v21, vcc, 0, v19, vcc
	global_store_dword v[20:21], v47, off offset:3456
	s_and_saveexec_b64 s[2:3], s[10:11]
	s_xor_b64 s[18:19], exec, s[2:3]
	s_cbranch_execz .LBB0_288
	s_waitcnt lgkmcnt(0)
	v_mul_f32_e32 v20, v220, v46
	v_mul_f32_e32 v21, v222, v22
	v_fmac_f32_e32 v20, v221, v44
	v_fmac_f32_e32 v21, v223, v23
.LBB0_288:
	s_andn2_saveexec_b64 s[18:19], s[18:19]
	s_cbranch_execz .LBB0_290
	s_waitcnt lgkmcnt(0)
	v_mul_f32_e32 v20, v236, v46
	v_mul_f32_e32 v21, v238, v22
	v_fma_f32 v20, -v237, v44, v20
	v_fma_f32 v21, -v239, v23, v21

; #define LAS __attribute__((address_space(3)))
; DI unsigned pk2(float lo, float hi) { f32x2 x = {lo, hi}; return __builtin_bit_cast(unsigned, __builtin_convertvector(x, bf16x2_t)); }
; DI float sum16(float v) { v += __shfl_xor(v, 8); v += __shfl_xor(v, 4); v += __shfl_xor(v, 2); v += __shfl_xor(v, 1); return v; }
; template <int HP> DI void rope2(f32x2& x, int hl, const LAS f32x2* cs) {
;   const float pa = __shfl_xor(x[0], HP), pb = __shfl_xor(x[1], HP);
;   if (hl < HP) { const f32x2 c0 = cs[2 * hl], c1 = cs[2 * hl + 1]; x[0] = x[0] * c0[0] - pa * c0[1]; x[1] = x[1] * c1[0] - pb * c1[1]; }
;   else if (hl < 2 * HP) { const f32x2 c0 = cs[2 * (hl - HP)], c1 = cs[2 * (hl - HP) + 1]; x[0] = x[0] * c0[0] + pa * c0[1]; x[1] = x[1] * c1[0] + pb * c1[1]; }
; }
; DI void post_unit(const Params& p, int l, int unit, LAS unsigned char* lds) {
;     ...
;       } else {
;         const float* gn = (s < 14) ? qnc : knc;
;         const float rs = rsqrtf(sum16(x[0] * x[0] + x[1] * x[1]) * (1.0f / 32.0f) + EPS);
;         x[0] *= rs * gn[2 * hl16]; x[1] *= rs * gn[2 * hl16 + 1]; rope2<2>(x, hl16, cs8 + t * 4);
;         if (s < 14) x *= LOG2E * 0.17677669529663687f;
;         *(unsigned*)pp = pk2(x[0], x[1]);
.LBB0_296:
	s_or_b64 exec, exec, s[18:19]
	s_mov_b32 s2, 0x3e8293ee
	s_waitcnt lgkmcnt(0)
	v_pk_mul_f32 v[20:21], v[22:23], s[2:3] op_sel_hi:[1,0]
	s_nop 0
	v_cvt_pk_bf16_f32 v22, v20, v21
	v_add_co_u32_e32 v20, vcc, 0xa003000, v18
	s_nop 1
	v_addc_co_u32_e32 v21, vcc, 0, v19, vcc
	global_store_dword v[20:21], v22, off offset:896
	s_waitcnt vmcnt(27)
	v_lshlrev_b32_e32 v20, 16, v42
	v_and_b32_e32 v21, 0xffff0000, v42
	v_pk_mul_f32 v[22:23], v[20:21], v[20:21]
	s_nop 0
	v_add_f32_e32 v22, v22, v23
	s_nop 1
	v_add_f32_dpp v22, v22, v22 row_ror:8 row_mask:0xf bank_mask:0xf
	s_nop 1
	v_add_f32_dpp v22, v22, v22 row_ror:4 row_mask:0xf bank_mask:0xf
	s_nop 1
	v_add_f32_dpp v22, v22, v22 quad_perm:[2,3,0,1] row_mask:0xf bank_mask:0xf
	s_nop 1
	v_add_f32_dpp v22, v22, v22 quad_perm:[1,0,3,2] row_mask:0xf bank_mask:0xf
	v_fmamk_f32 v22, v22, 0x3d000000, v170
	v_cmp_gt_f32_e32 vcc, s33, v22
	v_mul_f32_e32 v23, 0x4b800000, v22
	s_nop 0
	v_cndmask_b32_e32 v22, v22, v23, vcc
	v_rsq_f32_e32 v22, v22
	s_nop 0
	v_mul_f32_e32 v23, 0x45800000, v22
	v_cndmask_b32_e32 v22, v22, v23, vcc
	v_pk_mul_f32 v[22:23], v[6:7], v[22:23] op_sel_hi:[1,0]
	s_nop 0
	v_pk_mul_f32 v[22:23], v[22:23], v[20:21]
	ds_bpermute_b32 v20, v29, v22
	ds_bpermute_b32 v21, v29, v23
	s_and_saveexec_b64 s[2:3], s[6:7]
	s_xor_b64 s[18:19], exec, s[2:3]
	s_cbranch_execz .LBB0_300
	s_and_saveexec_b64 s[30:31], s[8:9]
	s_cbranch_execz .LBB0_299
	s_waitcnt lgkmcnt(0)
	v_mul_f32_e32 v22, v22, v228
	v_mul_f32_e32 v23, v23, v230
	v_fmac_f32_e32 v22, v229, v20
	v_fmac_f32_e32 v23, v21, v231

; #define LAS __attribute__((address_space(3)))
; DI unsigned pk2(float lo, float hi) { f32x2 x = {lo, hi}; return __builtin_bit_cast(unsigned, __builtin_convertvector(x, bf16x2_t)); }
; DI float sum16(float v) { v += __shfl_xor(v, 8); v += __shfl_xor(v, 4); v += __shfl_xor(v, 2); v += __shfl_xor(v, 1); return v; }
; template <int HP> DI void rope2(f32x2& x, int hl, const LAS f32x2* cs) {
;   const float pa = __shfl_xor(x[0], HP), pb = __shfl_xor(x[1], HP);
;   if (hl < HP) { const f32x2 c0 = cs[2 * hl], c1 = cs[2 * hl + 1]; x[0] = x[0] * c0[0] - pa * c0[1]; x[1] = x[1] * c1[0] - pb * c1[1]; }
;   else if (hl < 2 * HP) { const f32x2 c0 = cs[2 * (hl - HP)], c1 = cs[2 * (hl - HP) + 1]; x[0] = x[0] * c0[0] + pa * c0[1]; x[1] = x[1] * c1[0] + pb * c1[1]; }
; }
; DI void post_unit(const Params& p, int l, int unit, LAS unsigned char* lds) {
;     ...
;       } else {
;         const float* gn = (s < 14) ? qnc : knc;
;         const float rs = rsqrtf(sum16(x[0] * x[0] + x[1] * x[1]) * (1.0f / 32.0f) + EPS);
;         x[0] *= rs * gn[2 * hl16]; x[1] *= rs * gn[2 * hl16 + 1]; rope2<2>(x, hl16, cs8 + t * 4);
;         if (s < 14) x *= LOG2E * 0.17677669529663687f;
;         *(unsigned*)pp = pk2(x[0], x[1]);
.LBB0_300:
	s_andn2_saveexec_b64 s[18:19], s[18:19]
	s_cbranch_execz .LBB0_302
	s_waitcnt lgkmcnt(0)
	v_mul_f32_e32 v22, v22, v240
	v_mul_f32_e32 v23, v23, v242
	v_fma_f32 v22, -v241, v20, v22
	v_fma_f32 v23, -v21, v243, v23
.LBB0_302:
	s_or_b64 exec, exec, s[18:19]
	s_mov_b32 s2, 0x3e8293ee
	s_waitcnt lgkmcnt(0)
	v_pk_mul_f32 v[20:21], v[22:23], s[2:3] op_sel_hi:[1,0]
	s_nop 0
	v_cvt_pk_bf16_f32 v22, v20, v21
	v_add_co_u32_e32 v20, vcc, 0xa003000, v18
	s_nop 1
	v_addc_co_u32_e32 v21, vcc, 0, v19, vcc
	global_store_dword v[20:21], v22, off offset:1152
	s_waitcnt vmcnt(27)
	v_lshlrev_b32_e32 v20, 16, v41
	v_and_b32_e32 v21, 0xffff0000, v41
	v_pk_mul_f32 v[22:23], v[20:21], v[20:21]
	s_nop 0
	v_add_f32_e32 v22, v22, v23
	s_nop 1
	v_add_f32_dpp v22, v22, v22 row_ror:8 row_mask:0xf bank_mask:0xf
	s_nop 1
	v_add_f32_dpp v22, v22, v22 row_ror:4 row_mask:0xf bank_mask:0xf
	s_nop 1
	v_add_f32_dpp v22, v22, v22 quad_perm:[2,3,0,1] row_mask:0xf bank_mask:0xf
	s_nop 1
	v_add_f32_dpp v22, v22, v22 quad_perm:[1,0,3,2] row_mask:0xf bank_mask:0xf
	v_fmamk_f32 v22, v22, 0x3d000000, v170
	v_cmp_gt_f32_e32 vcc, s33, v22
	v_mul_f32_e32 v23, 0x4b800000, v22
	s_nop 0
	v_cndmask_b32_e32 v22, v22, v23, vcc
	v_rsq_f32_e32 v22, v22
	s_nop 0
	v_mul_f32_e32 v23, 0x45800000, v22
	v_cndmask_b32_e32 v22, v22, v23, vcc
	v_pk_mul_f32 v[22:23], v[8:9], v[22:23] op_sel_hi:[1,0]
	s_nop 0
	v_pk_mul_f32 v[22:23], v[22:23], v[20:21]
	ds_bpermute_b32 v20, v29, v22
	ds_bpermute_b32 v21, v29, v23
	s_and_saveexec_b64 s[2:3], s[6:7]
	s_xor_b64 s[18:19], exec, s[2:3]
	s_cbranch_execz .LBB0_306
	s_and_saveexec_b64 s[30:31], s[8:9]
	s_cbranch_execz .LBB0_305
	s_waitcnt lgkmcnt(0)
	v_mul_f32_e32 v22, v22, v228
	v_mul_f32_e32 v23, v23, v230
	v_fmac_f32_e32 v22, v229, v20
	v_fmac_f32_e32 v23, v21, v231

; #define LAS __attribute__((address_space(3)))
; DI unsigned pk2(float lo, float hi) { f32x2 x = {lo, hi}; return __builtin_bit_cast(unsigned, __builtin_convertvector(x, bf16x2_t)); }
; DI float sum16(float v) { v += __shfl_xor(v, 8); v += __shfl_xor(v, 4); v += __shfl_xor(v, 2); v += __shfl_xor(v, 1); return v; }
; template <int HP> DI void rope2(f32x2& x, int hl, const LAS f32x2* cs) {
;   const float pa = __shfl_xor(x[0], HP), pb = __shfl_xor(x[1], HP);
;   if (hl < HP) { const f32x2 c0 = cs[2 * hl], c1 = cs[2 * hl + 1]; x[0] = x[0] * c0[0] - pa * c0[1]; x[1] = x[1] * c1[0] - pb * c1[1]; }
;   else if (hl < 2 * HP) { const f32x2 c0 = cs[2 * (hl - HP)], c1 = cs[2 * (hl - HP) + 1]; x[0] = x[0] * c0[0] + pa * c0[1]; x[1] = x[1] * c1[0] + pb * c1[1]; }
; }
; DI void post_unit(const Params& p, int l, int unit, LAS unsigned char* lds) {
;     ...
;       } else {
;         const float* gn = (s < 14) ? qnc : knc;
;         const float rs = rsqrtf(sum16(x[0] * x[0] + x[1] * x[1]) * (1.0f / 32.0f) + EPS);
;         x[0] *= rs * gn[2 * hl16]; x[1] *= rs * gn[2 * hl16 + 1]; rope2<2>(x, hl16, cs8 + t * 4);
;         if (s < 14) x *= LOG2E * 0.17677669529663687f;
;         *(unsigned*)pp = pk2(x[0], x[1]);
.LBB0_308:
	s_or_b64 exec, exec, s[18:19]
	s_waitcnt lgkmcnt(1)
	v_add_co_u32_e32 v20, vcc, 0xa003000, v18
	v_cvt_pk_bf16_f32 v22, v22, v23
	s_waitcnt lgkmcnt(0)
	v_addc_co_u32_e32 v21, vcc, 0, v19, vcc
	global_store_dword v[20:21], v22, off offset:1408
	s_waitcnt vmcnt(27)
	v_lshlrev_b32_e32 v20, 16, v3
	v_and_b32_e32 v21, 0xffff0000, v3
	v_pk_mul_f32 v[22:23], v[20:21], v[20:21]
	s_nop 0
	v_add_f32_e32 v3, v22, v23
	s_nop 1
	v_add_f32_dpp v3, v3, v3 row_ror:8 row_mask:0xf bank_mask:0xf
	s_nop 1
	v_add_f32_dpp v3, v3, v3 row_ror:4 row_mask:0xf bank_mask:0xf
	s_nop 1
	v_add_f32_dpp v3, v3, v3 quad_perm:[2,3,0,1] row_mask:0xf bank_mask:0xf
	s_nop 1
	v_add_f32_dpp v3, v3, v3 quad_perm:[1,0,3,2] row_mask:0xf bank_mask:0xf
	v_fmamk_f32 v3, v3, 0x3d000000, v170
	v_cmp_gt_f32_e32 vcc, s33, v3
	v_mul_f32_e32 v22, 0x4b800000, v3
	s_nop 0
	v_cndmask_b32_e32 v3, v3, v22, vcc
	v_rsq_f32_e32 v3, v3
	s_nop 0
	v_mul_f32_e32 v22, 0x45800000, v3
	v_cndmask_b32_e32 v22, v3, v22, vcc
	v_pk_mul_f32 v[22:23], v[8:9], v[22:23] op_sel_hi:[1,0]
	s_nop 0
	v_pk_mul_f32 v[22:23], v[22:23], v[20:21]
	ds_bpermute_b32 v3, v29, v22
	ds_bpermute_b32 v21, v29, v23
	s_and_saveexec_b64 s[2:3], s[6:7]
	s_xor_b64 s[18:19], exec, s[2:3]
	s_cbranch_execz .LBB0_312
	s_and_saveexec_b64 s[30:31], s[8:9]
	s_cbranch_execz .LBB0_311
	v_mov_b32_e32 v20, v23
	s_waitcnt lgkmcnt(0)
	v_mul_f32_e32 v22, v22, v228
	v_mul_f32_e32 v23, v20, v230
	v_fmac_f32_e32 v22, v229, v3
	v_fmac_f32_e32 v23, v21, v231

; #define LAS __attribute__((address_space(3)))
; DI unsigned pk2(float lo, float hi) { f32x2 x = {lo, hi}; return __builtin_bit_cast(unsigned, __builtin_convertvector(x, bf16x2_t)); }
; DI float sum16(float v) { v += __shfl_xor(v, 8); v += __shfl_xor(v, 4); v += __shfl_xor(v, 2); v += __shfl_xor(v, 1); return v; }
; template <int HP> DI void rope2(f32x2& x, int hl, const LAS f32x2* cs) {
;   const float pa = __shfl_xor(x[0], HP), pb = __shfl_xor(x[1], HP);
;   if (hl < HP) { const f32x2 c0 = cs[2 * hl], c1 = cs[2 * hl + 1]; x[0] = x[0] * c0[0] - pa * c0[1]; x[1] = x[1] * c1[0] - pb * c1[1]; }
;   else if (hl < 2 * HP) { const f32x2 c0 = cs[2 * (hl - HP)], c1 = cs[2 * (hl - HP) + 1]; x[0] = x[0] * c0[0] + pa * c0[1]; x[1] = x[1] * c1[0] + pb * c1[1]; }
; }
; DI void post_unit(const Params& p, int l, int unit, LAS unsigned char* lds) {
;     ...
;       } else {
;         const float* gn = (s < 14) ? qnc : knc;
;         const float rs = rsqrtf(sum16(x[0] * x[0] + x[1] * x[1]) * (1.0f / 32.0f) + EPS);
;         x[0] *= rs * gn[2 * hl16]; x[1] *= rs * gn[2 * hl16 + 1]; rope2<2>(x, hl16, cs8 + t * 4);
;         if (s < 14) x *= LOG2E * 0.17677669529663687f;
;         *(unsigned*)pp = pk2(x[0], x[1]);
.LBB0_312:
	s_andn2_saveexec_b64 s[18:19], s[18:19]
	s_cbranch_execz .LBB0_149
	v_mov_b32_e32 v20, v23
	s_waitcnt lgkmcnt(0)
	v_mul_f32_e32 v22, v22, v240
	v_mul_f32_e32 v23, v20, v242
	v_fma_f32 v22, -v241, v3, v22
	v_fma_f32 v23, -v21, v243, v23
	s_branch .LBB0_149

; #define LAS __attribute__((address_space(3)))
; template <int HP> DI void rope2(f32x2& x, int hl, const LAS f32x2* cs) {
;   const float pa = __shfl_xor(x[0], HP), pb = __shfl_xor(x[1], HP);
;   if (hl < HP) { const f32x2 c0 = cs[2 * hl], c1 = cs[2 * hl + 1]; x[0] = x[0] * c0[0] - pa * c0[1]; x[1] = x[1] * c1[0] - pb * c1[1]; }
;   else if (hl < 2 * HP) { const f32x2 c0 = cs[2 * (hl - HP)], c1 = cs[2 * (hl - HP) + 1]; x[0] = x[0] * c0[0] + pa * c0[1]; x[1] = x[1] * c1[0] + pb * c1[1]; }
; }
.LBB0_315:
	ds_read_b128 v[68:71], v49 offset:64
	s_waitcnt lgkmcnt(0)
	v_mul_f32_e32 v20, v20, v68
	v_mul_f32_e32 v21, v70, v21
	v_fma_f32 v20, -v69, v22, v20
	v_fma_f32 v21, -v71, v23, v21
	s_or_b64 exec, exec, s[18:19]
	s_and_saveexec_b64 s[18:19], s[16:17]
	s_cbranch_execnz .LBB0_191
	s_branch .LBB0_192

; #define LAS __attribute__((address_space(3)))
; template <int HP> DI void rope2(f32x2& x, int hl, const LAS f32x2* cs) {
;   const float pa = __shfl_xor(x[0], HP), pb = __shfl_xor(x[1], HP);
;   if (hl < HP) { const f32x2 c0 = cs[2 * hl], c1 = cs[2 * hl + 1]; x[0] = x[0] * c0[0] - pa * c0[1]; x[1] = x[1] * c1[0] - pb * c1[1]; }
;   else if (hl < 2 * HP) { const f32x2 c0 = cs[2 * (hl - HP)], c1 = cs[2 * (hl - HP) + 1]; x[0] = x[0] * c0[0] + pa * c0[1]; x[1] = x[1] * c1[0] + pb * c1[1]; }
; }
.LBB0_317:
	ds_read_b128 v[48:51], v49 offset:128
	s_waitcnt lgkmcnt(0)
	v_mul_f32_e32 v20, v20, v48
	v_mul_f32_e32 v21, v50, v21
	v_fma_f32 v20, -v49, v22, v20
	v_fma_f32 v21, -v51, v23, v21
	s_or_b64 exec, exec, s[18:19]
	s_and_saveexec_b64 s[18:19], s[16:17]
	s_cbranch_execnz .LBB0_273
	s_branch .LBB0_274
